# P1 pair jobs: prefetched first slab is waited with a counted vmcnt(16), no longer behind the previous job's 16 epilogue stores
# baseline (speedup 1.0000x reference)
; template <bool SWAP, class Epi>
; DI void gemm_tile(const u16* __restrict__ A, int lda, const u16* __restrict__ Bw, int ldb, int K, char* lds, Epi epi) {
;     ...
;   gload(0, ra0, rb0);
;   lstore(0, ra0, rb0);
;   gload(1, ra1, rb1);
;   __syncthreads();
;   for (int kt = 0; kt < nk; kt += 2) {
;     if (kt + 2 < nk) gload(kt + 2, ra0, rb0);
;     compute(0);
;     lstore(1, ra1, rb1);
;     __syncthreads();
;     if (kt + 3 < nk) gload(kt + 3, ra1, rb1);
;     compute(1);
;     if (kt + 2 < nk) lstore(0, ra0, rb0);
;     __syncthreads();
.Lpp_pfd:
	s_mov_b32 s13, s100
	s_mov_b32 s100, 0
	v_add_u32_e32 v208, 0x80, v208
	v_add_u32_e32 v209, 0x80, v209
	v_and_b32_e32 v0, 31, v1
	v_lshrrev_b32_e32 v2, 1, v0
	v_and_b32_e32 v2, 7, v2
	v_lshrrev_b32_e32 v1, 5, v1
	v_xor_b32_e32 v2, v2, v1
	v_lshlrev_b32_e32 v0, 7, v0
	s_and_b32 s0, s3, 3
	s_lshr_b32 s1, s3, 2
	s_lshl_b32 s10, s0, 13
	s_lshl_b32 s11, s1, 13
	s_add_i32 s11, s11, 0x10000
	v_xor_b32_e32 v214, 0, v2
	v_lshl_add_u32 v214, v214, 4, v0
	v_add_u32_e32 v210, s10, v214
	v_add_u32_e32 v214, s11, v214
	v_xor_b32_e32 v215, 2, v2
	v_lshl_add_u32 v215, v215, 4, v0
	v_add_u32_e32 v211, s10, v215
	v_add_u32_e32 v215, s11, v215
	v_xor_b32_e32 v216, 4, v2
	v_lshl_add_u32 v216, v216, 4, v0
	v_add_u32_e32 v212, s10, v216
	v_add_u32_e32 v216, s11, v216
	v_xor_b32_e32 v217, 6, v2
	v_lshl_add_u32 v217, v217, 4, v0
	v_add_u32_e32 v213, s10, v217
	v_add_u32_e32 v217, s11, v217
	s_lshl_b32 s12, s26, 8
	s_lshl_b32 s0, s0, 6
	s_add_i32 s12, s12, s0
	v_lshrrev_b32_e32 v0, 7, v0
	v_add_u32_e32 v0, s12, v0
	v_mul_u32_u24_e32 v0, 0x2a00, v0
	s_lshl_b32 s12, s2, 8
	s_lshl_b32 s1, s1, 7
	s_add_i32 s12, s12, s1
	v_lshlrev_b32_e32 v1, 4, v1
	v_add3_u32 v218, v0, v1, s12
	v_add_u32_e32 v219, 0x54000, v218
	s_cmp_eq_u32 s13, 1
	s_cbranch_scc1 .Lpp_w16
	s_waitcnt vmcnt(0)
	s_branch .Lpp_w0
.Lpp_w16:
	s_waitcnt vmcnt(16)
.Lpp_w0:
	s_waitcnt lgkmcnt(0)
	s_barrier
	ds_read_b128 v[132:135], v210 offset:0
	ds_read_b128 v[136:139], v210 offset:4096
	ds_read_b128 v[140:143], v214 offset:0
	ds_read_b128 v[144:147], v214 offset:4096
	ds_read_b128 v[148:151], v214 offset:16384
	ds_read_b128 v[158:161], v214 offset:20480
	s_mov_b32 m0, s45
	s_nop 0
	global_load_lds_dwordx4 v208, s[68:69]
	global_load_lds_dwordx4 v209, s[70:71] offset:1024
	global_load_lds_dwordx4 v208, s[72:73] offset:2048
	global_load_lds_dwordx4 v209, s[74:75] offset:3072
	ds_read_b128 v[162:165], v211 offset:0
	ds_read_b128 v[168:171], v211 offset:4096
	ds_read_b128 v[172:175], v215 offset:0
	ds_read_b128 v[176:179], v215 offset:4096
	ds_read_b128 v[180:183], v215 offset:16384
	ds_read_b128 v[184:187], v215 offset:20480
	s_waitcnt lgkmcnt(6)
	v_mfma_f32_32x32x16_bf16 v[4:19], v[140:143], v[132:135], 0
	v_mfma_f32_32x32x16_bf16 v[68:83], v[140:143], v[136:139], 0
	v_mfma_f32_32x32x16_bf16 v[20:35], v[144:147], v[132:135], 0
	v_mfma_f32_32x32x16_bf16 v[84:99], v[144:147], v[136:139], 0
	v_mfma_f32_32x32x16_bf16 v[36:51], v[148:151], v[132:135], 0
	v_mfma_f32_32x32x16_bf16 v[100:115], v[148:151], v[136:139], 0
	v_mfma_f32_32x32x16_bf16 v[52:67], v[158:161], v[132:135], 0
	v_mfma_f32_32x32x16_bf16 v[116:131], v[158:161], v[136:139], 0
	s_mov_b32 m0, s47
	s_nop 0
	global_load_lds_dwordx4 v208, s[76:77]
	global_load_lds_dwordx4 v209, s[78:79] offset:1024
	global_load_lds_dwordx4 v208, s[80:81] offset:2048
	global_load_lds_dwordx4 v209, s[82:83] offset:3072
	v_add_u32_e32 v208, 0x80, v208
	v_add_u32_e32 v209, 0x80, v209
	ds_read_b128 v[132:135], v212 offset:0
	ds_read_b128 v[136:139], v212 offset:4096
	ds_read_b128 v[140:143], v216 offset:0
	ds_read_b128 v[144:147], v216 offset:4096
	ds_read_b128 v[148:151], v216 offset:16384
	ds_read_b128 v[158:161], v216 offset:20480
	s_waitcnt lgkmcnt(6)
	v_mfma_f32_32x32x16_bf16 v[4:19], v[172:175], v[162:165], v[4:19]
	v_mfma_f32_32x32x16_bf16 v[68:83], v[172:175], v[168:171], v[68:83]
	v_mfma_f32_32x32x16_bf16 v[20:35], v[176:179], v[162:165], v[20:35]
	v_mfma_f32_32x32x16_bf16 v[84:99], v[176:179], v[168:171], v[84:99]
	v_mfma_f32_32x32x16_bf16 v[36:51], v[180:183], v[162:165], v[36:51]
	v_mfma_f32_32x32x16_bf16 v[100:115], v[180:183], v[168:171], v[100:115]
	v_mfma_f32_32x32x16_bf16 v[52:67], v[184:187], v[162:165], v[52:67]
	v_mfma_f32_32x32x16_bf16 v[116:131], v[184:187], v[168:171], v[116:131]
	ds_read_b128 v[162:165], v213 offset:0
	ds_read_b128 v[168:171], v213 offset:4096
	ds_read_b128 v[172:175], v217 offset:0
	ds_read_b128 v[176:179], v217 offset:4096
	ds_read_b128 v[180:183], v217 offset:16384
	ds_read_b128 v[184:187], v217 offset:20480
	s_waitcnt lgkmcnt(6)
	v_mfma_f32_32x32x16_bf16 v[4:19], v[140:143], v[132:135], v[4:19]
	v_mfma_f32_32x32x16_bf16 v[68:83], v[140:143], v[136:139], v[68:83]
	v_mfma_f32_32x32x16_bf16 v[20:35], v[144:147], v[132:135], v[20:35]
	v_mfma_f32_32x32x16_bf16 v[84:99], v[144:147], v[136:139], v[84:99]
	v_mfma_f32_32x32x16_bf16 v[36:51], v[148:151], v[132:135], v[36:51]
	v_mfma_f32_32x32x16_bf16 v[100:115], v[148:151], v[136:139], v[100:115]
	v_mfma_f32_32x32x16_bf16 v[52:67], v[158:161], v[132:135], v[52:67]
	v_mfma_f32_32x32x16_bf16 v[116:131], v[158:161], v[136:139], v[116:131]
	s_waitcnt lgkmcnt(0)
	v_mfma_f32_32x32x16_bf16 v[4:19], v[172:175], v[162:165], v[4:19]
	v_mfma_f32_32x32x16_bf16 v[68:83], v[172:175], v[168:171], v[68:83]
	v_mfma_f32_32x32x16_bf16 v[20:35], v[176:179], v[162:165], v[20:35]
	v_mfma_f32_32x32x16_bf16 v[84:99], v[176:179], v[168:171], v[84:99]
	v_mfma_f32_32x32x16_bf16 v[36:51], v[180:183], v[162:165], v[36:51]
	v_mfma_f32_32x32x16_bf16 v[100:115], v[180:183], v[168:171], v[100:115]
	v_mfma_f32_32x32x16_bf16 v[52:67], v[184:187], v[162:165], v[52:67]
	v_mfma_f32_32x32x16_bf16 v[116:131], v[184:187], v[168:171], v[116:131]
	s_waitcnt vmcnt(0) lgkmcnt(0)
	s_barrier
; template <bool SWAP, class Epi>
; DI void gemm_tile(const u16* __restrict__ A, int lda, const u16* __restrict__ Bw, int ldb, int K, char* lds, Epi epi) {
;     ...
;   for (int kt = 0; kt < nk; kt += 2) {
;     if (kt + 2 < nk) gload(kt + 2, ra0, rb0);
;     compute(0);
;     lstore(1, ra1, rb1);
;     __syncthreads();
;     if (kt + 3 < nk) gload(kt + 3, ra1, rb1);
;     compute(1);
;     if (kt + 2 < nk) lstore(0, ra0, rb0);
;     __syncthreads();
	ds_read_b128 v[132:135], v210 offset:32768
	ds_read_b128 v[136:139], v210 offset:36864
	ds_read_b128 v[140:143], v214 offset:32768
	ds_read_b128 v[144:147], v214 offset:36864
	ds_read_b128 v[148:151], v214 offset:49152
	ds_read_b128 v[158:161], v214 offset:53248
	s_mov_b32 m0, s44
	s_nop 0
	global_load_lds_dwordx4 v208, s[68:69]
	global_load_lds_dwordx4 v209, s[70:71] offset:1024
	global_load_lds_dwordx4 v208, s[72:73] offset:2048
	global_load_lds_dwordx4 v209, s[74:75] offset:3072
	ds_read_b128 v[162:165], v211 offset:32768
	ds_read_b128 v[168:171], v211 offset:36864
	ds_read_b128 v[172:175], v215 offset:32768
	ds_read_b128 v[176:179], v215 offset:36864
	ds_read_b128 v[180:183], v215 offset:49152
	ds_read_b128 v[184:187], v215 offset:53248
	s_waitcnt lgkmcnt(6)
	v_mfma_f32_32x32x16_bf16 v[4:19], v[140:143], v[132:135], v[4:19]
	v_mfma_f32_32x32x16_bf16 v[68:83], v[140:143], v[136:139], v[68:83]
	v_mfma_f32_32x32x16_bf16 v[20:35], v[144:147], v[132:135], v[20:35]
	v_mfma_f32_32x32x16_bf16 v[84:99], v[144:147], v[136:139], v[84:99]
	v_mfma_f32_32x32x16_bf16 v[36:51], v[148:151], v[132:135], v[36:51]
	v_mfma_f32_32x32x16_bf16 v[100:115], v[148:151], v[136:139], v[100:115]
	v_mfma_f32_32x32x16_bf16 v[52:67], v[158:161], v[132:135], v[52:67]
	v_mfma_f32_32x32x16_bf16 v[116:131], v[158:161], v[136:139], v[116:131]
	s_mov_b32 m0, s46
	s_nop 0
	global_load_lds_dwordx4 v208, s[76:77]
	global_load_lds_dwordx4 v209, s[78:79] offset:1024
	global_load_lds_dwordx4 v208, s[80:81] offset:2048
	global_load_lds_dwordx4 v209, s[82:83] offset:3072
	v_add_u32_e32 v208, 0x80, v208
	v_add_u32_e32 v209, 0x80, v209
	ds_read_b128 v[132:135], v212 offset:32768
	ds_read_b128 v[136:139], v212 offset:36864
	ds_read_b128 v[140:143], v216 offset:32768
	ds_read_b128 v[144:147], v216 offset:36864
	ds_read_b128 v[148:151], v216 offset:49152
	ds_read_b128 v[158:161], v216 offset:53248
	s_waitcnt lgkmcnt(6)
	v_mfma_f32_32x32x16_bf16 v[4:19], v[172:175], v[162:165], v[4:19]
	v_mfma_f32_32x32x16_bf16 v[68:83], v[172:175], v[168:171], v[68:83]
	v_mfma_f32_32x32x16_bf16 v[20:35], v[176:179], v[162:165], v[20:35]
	v_mfma_f32_32x32x16_bf16 v[84:99], v[176:179], v[168:171], v[84:99]
	v_mfma_f32_32x32x16_bf16 v[36:51], v[180:183], v[162:165], v[36:51]
	v_mfma_f32_32x32x16_bf16 v[100:115], v[180:183], v[168:171], v[100:115]
	v_mfma_f32_32x32x16_bf16 v[52:67], v[184:187], v[162:165], v[52:67]
	v_mfma_f32_32x32x16_bf16 v[116:131], v[184:187], v[168:171], v[116:131]
	ds_read_b128 v[162:165], v213 offset:32768
	ds_read_b128 v[168:171], v213 offset:36864
	ds_read_b128 v[172:175], v217 offset:32768
	ds_read_b128 v[176:179], v217 offset:36864
	ds_read_b128 v[180:183], v217 offset:49152
	ds_read_b128 v[184:187], v217 offset:53248
	s_waitcnt lgkmcnt(6)
	v_mfma_f32_32x32x16_bf16 v[4:19], v[140:143], v[132:135], v[4:19]
	v_mfma_f32_32x32x16_bf16 v[68:83], v[140:143], v[136:139], v[68:83]
	v_mfma_f32_32x32x16_bf16 v[20:35], v[144:147], v[132:135], v[20:35]
	v_mfma_f32_32x32x16_bf16 v[84:99], v[144:147], v[136:139], v[84:99]
	v_mfma_f32_32x32x16_bf16 v[36:51], v[148:151], v[132:135], v[36:51]
	v_mfma_f32_32x32x16_bf16 v[100:115], v[148:151], v[136:139], v[100:115]
	v_mfma_f32_32x32x16_bf16 v[52:67], v[158:161], v[132:135], v[52:67]
	v_mfma_f32_32x32x16_bf16 v[116:131], v[158:161], v[136:139], v[116:131]
	s_waitcnt lgkmcnt(0)
	v_mfma_f32_32x32x16_bf16 v[4:19], v[172:175], v[162:165], v[4:19]
	v_mfma_f32_32x32x16_bf16 v[68:83], v[172:175], v[168:171], v[68:83]
	v_mfma_f32_32x32x16_bf16 v[20:35], v[176:179], v[162:165], v[20:35]
	v_mfma_f32_32x32x16_bf16 v[84:99], v[176:179], v[168:171], v[84:99]
	v_mfma_f32_32x32x16_bf16 v[36:51], v[180:183], v[162:165], v[36:51]
	v_mfma_f32_32x32x16_bf16 v[100:115], v[180:183], v[168:171], v[100:115]
	v_mfma_f32_32x32x16_bf16 v[52:67], v[184:187], v[162:165], v[52:67]
	v_mfma_f32_32x32x16_bf16 v[116:131], v[184:187], v[168:171], v[116:131]
	s_waitcnt vmcnt(0) lgkmcnt(0)
	s_barrier
	ds_read_b128 v[132:135], v210 offset:0
	ds_read_b128 v[136:139], v210 offset:4096
	ds_read_b128 v[140:143], v214 offset:0
	ds_read_b128 v[144:147], v214 offset:4096
	ds_read_b128 v[148:151], v214 offset:16384
	ds_read_b128 v[158:161], v214 offset:20480
	s_mov_b32 m0, s45
	s_nop 0
	global_load_lds_dwordx4 v208, s[68:69]
	global_load_lds_dwordx4 v209, s[70:71] offset:1024
	global_load_lds_dwordx4 v208, s[72:73] offset:2048
	global_load_lds_dwordx4 v209, s[74:75] offset:3072
	ds_read_b128 v[162:165], v211 offset:0
	ds_read_b128 v[168:171], v211 offset:4096
	ds_read_b128 v[172:175], v215 offset:0
	ds_read_b128 v[176:179], v215 offset:4096
	ds_read_b128 v[180:183], v215 offset:16384
	ds_read_b128 v[184:187], v215 offset:20480
	s_waitcnt lgkmcnt(6)
	v_mfma_f32_32x32x16_bf16 v[4:19], v[140:143], v[132:135], v[4:19]
	v_mfma_f32_32x32x16_bf16 v[68:83], v[140:143], v[136:139], v[68:83]
	v_mfma_f32_32x32x16_bf16 v[20:35], v[144:147], v[132:135], v[20:35]
	v_mfma_f32_32x32x16_bf16 v[84:99], v[144:147], v[136:139], v[84:99]
	v_mfma_f32_32x32x16_bf16 v[36:51], v[148:151], v[132:135], v[36:51]
	v_mfma_f32_32x32x16_bf16 v[100:115], v[148:151], v[136:139], v[100:115]
	v_mfma_f32_32x32x16_bf16 v[52:67], v[158:161], v[132:135], v[52:67]
	v_mfma_f32_32x32x16_bf16 v[116:131], v[158:161], v[136:139], v[116:131]
	s_mov_b32 m0, s47
	s_nop 0
	global_load_lds_dwordx4 v208, s[76:77]
	global_load_lds_dwordx4 v209, s[78:79] offset:1024
	global_load_lds_dwordx4 v208, s[80:81] offset:2048
	global_load_lds_dwordx4 v209, s[82:83] offset:3072
	v_add_u32_e32 v208, 0x80, v208
	v_add_u32_e32 v209, 0x80, v209
	ds_read_b128 v[132:135], v212 offset:0
	ds_read_b128 v[136:139], v212 offset:4096
	ds_read_b128 v[140:143], v216 offset:0
	ds_read_b128 v[144:147], v216 offset:4096
	ds_read_b128 v[148:151], v216 offset:16384
	ds_read_b128 v[158:161], v216 offset:20480
	s_waitcnt lgkmcnt(6)
; template <bool SWAP, class Epi>
; DI void gemm_tile(const u16* __restrict__ A, int lda, const u16* __restrict__ Bw, int ldb, int K, char* lds, Epi epi) {
;     ...
;   for (int kt = 0; kt < nk; kt += 2) {
;     if (kt + 2 < nk) gload(kt + 2, ra0, rb0);
;     compute(0);
;     lstore(1, ra1, rb1);
;     __syncthreads();
;     if (kt + 3 < nk) gload(kt + 3, ra1, rb1);
;     compute(1);
;     if (kt + 2 < nk) lstore(0, ra0, rb0);
;     __syncthreads();
	v_mfma_f32_32x32x16_bf16 v[4:19], v[172:175], v[162:165], v[4:19]
	v_mfma_f32_32x32x16_bf16 v[68:83], v[172:175], v[168:171], v[68:83]
	v_mfma_f32_32x32x16_bf16 v[20:35], v[176:179], v[162:165], v[20:35]
	v_mfma_f32_32x32x16_bf16 v[84:99], v[176:179], v[168:171], v[84:99]
	v_mfma_f32_32x32x16_bf16 v[36:51], v[180:183], v[162:165], v[36:51]
	v_mfma_f32_32x32x16_bf16 v[100:115], v[180:183], v[168:171], v[100:115]
	v_mfma_f32_32x32x16_bf16 v[52:67], v[184:187], v[162:165], v[52:67]
	v_mfma_f32_32x32x16_bf16 v[116:131], v[184:187], v[168:171], v[116:131]
	ds_read_b128 v[162:165], v213 offset:0
	ds_read_b128 v[168:171], v213 offset:4096
	ds_read_b128 v[172:175], v217 offset:0
	ds_read_b128 v[176:179], v217 offset:4096
	ds_read_b128 v[180:183], v217 offset:16384
	ds_read_b128 v[184:187], v217 offset:20480
	s_waitcnt lgkmcnt(6)
	v_mfma_f32_32x32x16_bf16 v[4:19], v[140:143], v[132:135], v[4:19]
	v_mfma_f32_32x32x16_bf16 v[68:83], v[140:143], v[136:139], v[68:83]
	v_mfma_f32_32x32x16_bf16 v[20:35], v[144:147], v[132:135], v[20:35]
	v_mfma_f32_32x32x16_bf16 v[84:99], v[144:147], v[136:139], v[84:99]
	v_mfma_f32_32x32x16_bf16 v[36:51], v[148:151], v[132:135], v[36:51]
	v_mfma_f32_32x32x16_bf16 v[100:115], v[148:151], v[136:139], v[100:115]
	v_mfma_f32_32x32x16_bf16 v[52:67], v[158:161], v[132:135], v[52:67]
	v_mfma_f32_32x32x16_bf16 v[116:131], v[158:161], v[136:139], v[116:131]
	s_waitcnt lgkmcnt(0)
	v_mfma_f32_32x32x16_bf16 v[4:19], v[172:175], v[162:165], v[4:19]
	v_mfma_f32_32x32x16_bf16 v[68:83], v[172:175], v[168:171], v[68:83]
	v_mfma_f32_32x32x16_bf16 v[20:35], v[176:179], v[162:165], v[20:35]
	v_mfma_f32_32x32x16_bf16 v[84:99], v[176:179], v[168:171], v[84:99]
	v_mfma_f32_32x32x16_bf16 v[36:51], v[180:183], v[162:165], v[36:51]
	v_mfma_f32_32x32x16_bf16 v[100:115], v[180:183], v[168:171], v[100:115]
	v_mfma_f32_32x32x16_bf16 v[52:67], v[184:187], v[162:165], v[52:67]
	v_mfma_f32_32x32x16_bf16 v[116:131], v[184:187], v[168:171], v[116:131]
	s_waitcnt vmcnt(0) lgkmcnt(0)
	s_barrier
	ds_read_b128 v[132:135], v210 offset:32768
	ds_read_b128 v[136:139], v210 offset:36864
	ds_read_b128 v[140:143], v214 offset:32768
	ds_read_b128 v[144:147], v214 offset:36864
	ds_read_b128 v[148:151], v214 offset:49152
	ds_read_b128 v[158:161], v214 offset:53248
	s_mov_b32 m0, s44
	s_nop 0
	global_load_lds_dwordx4 v208, s[68:69]
	global_load_lds_dwordx4 v209, s[70:71] offset:1024
	global_load_lds_dwordx4 v208, s[72:73] offset:2048
	global_load_lds_dwordx4 v209, s[74:75] offset:3072
	ds_read_b128 v[162:165], v211 offset:32768
	ds_read_b128 v[168:171], v211 offset:36864
	ds_read_b128 v[172:175], v215 offset:32768
	ds_read_b128 v[176:179], v215 offset:36864
	ds_read_b128 v[180:183], v215 offset:49152
	ds_read_b128 v[184:187], v215 offset:53248
	s_waitcnt lgkmcnt(6)
	v_mfma_f32_32x32x16_bf16 v[4:19], v[140:143], v[132:135], v[4:19]
	v_mfma_f32_32x32x16_bf16 v[68:83], v[140:143], v[136:139], v[68:83]
	v_mfma_f32_32x32x16_bf16 v[20:35], v[144:147], v[132:135], v[20:35]
	v_mfma_f32_32x32x16_bf16 v[84:99], v[144:147], v[136:139], v[84:99]
	v_mfma_f32_32x32x16_bf16 v[36:51], v[148:151], v[132:135], v[36:51]
	v_mfma_f32_32x32x16_bf16 v[100:115], v[148:151], v[136:139], v[100:115]
	v_mfma_f32_32x32x16_bf16 v[52:67], v[158:161], v[132:135], v[52:67]
	v_mfma_f32_32x32x16_bf16 v[116:131], v[158:161], v[136:139], v[116:131]
	s_mov_b32 m0, s46
	s_nop 0
	global_load_lds_dwordx4 v208, s[76:77]
	global_load_lds_dwordx4 v209, s[78:79] offset:1024
	global_load_lds_dwordx4 v208, s[80:81] offset:2048
	global_load_lds_dwordx4 v209, s[82:83] offset:3072
	v_add_u32_e32 v208, 0x80, v208
	v_add_u32_e32 v209, 0x80, v209
	ds_read_b128 v[132:135], v212 offset:32768
	ds_read_b128 v[136:139], v212 offset:36864
	ds_read_b128 v[140:143], v216 offset:32768
	ds_read_b128 v[144:147], v216 offset:36864
	ds_read_b128 v[148:151], v216 offset:49152
	ds_read_b128 v[158:161], v216 offset:53248
	s_waitcnt lgkmcnt(6)
	v_mfma_f32_32x32x16_bf16 v[4:19], v[172:175], v[162:165], v[4:19]
	v_mfma_f32_32x32x16_bf16 v[68:83], v[172:175], v[168:171], v[68:83]
	v_mfma_f32_32x32x16_bf16 v[20:35], v[176:179], v[162:165], v[20:35]
	v_mfma_f32_32x32x16_bf16 v[84:99], v[176:179], v[168:171], v[84:99]
	v_mfma_f32_32x32x16_bf16 v[36:51], v[180:183], v[162:165], v[36:51]
	v_mfma_f32_32x32x16_bf16 v[100:115], v[180:183], v[168:171], v[100:115]
	v_mfma_f32_32x32x16_bf16 v[52:67], v[184:187], v[162:165], v[52:67]
	v_mfma_f32_32x32x16_bf16 v[116:131], v[184:187], v[168:171], v[116:131]
	ds_read_b128 v[162:165], v213 offset:32768
	ds_read_b128 v[168:171], v213 offset:36864
	ds_read_b128 v[172:175], v217 offset:32768
	ds_read_b128 v[176:179], v217 offset:36864
	ds_read_b128 v[180:183], v217 offset:49152
	ds_read_b128 v[184:187], v217 offset:53248
	s_waitcnt lgkmcnt(6)
	v_mfma_f32_32x32x16_bf16 v[4:19], v[140:143], v[132:135], v[4:19]
	v_mfma_f32_32x32x16_bf16 v[68:83], v[140:143], v[136:139], v[68:83]
	v_mfma_f32_32x32x16_bf16 v[20:35], v[144:147], v[132:135], v[20:35]
	v_mfma_f32_32x32x16_bf16 v[84:99], v[144:147], v[136:139], v[84:99]
	v_mfma_f32_32x32x16_bf16 v[36:51], v[148:151], v[132:135], v[36:51]
	v_mfma_f32_32x32x16_bf16 v[100:115], v[148:151], v[136:139], v[100:115]
	v_mfma_f32_32x32x16_bf16 v[52:67], v[158:161], v[132:135], v[52:67]
	v_mfma_f32_32x32x16_bf16 v[116:131], v[158:161], v[136:139], v[116:131]
	s_waitcnt lgkmcnt(0)
	v_mfma_f32_32x32x16_bf16 v[4:19], v[172:175], v[162:165], v[4:19]
	v_mfma_f32_32x32x16_bf16 v[68:83], v[172:175], v[168:171], v[68:83]
	v_mfma_f32_32x32x16_bf16 v[20:35], v[176:179], v[162:165], v[20:35]
	v_mfma_f32_32x32x16_bf16 v[84:99], v[176:179], v[168:171], v[84:99]
	v_mfma_f32_32x32x16_bf16 v[36:51], v[180:183], v[162:165], v[36:51]
	v_mfma_f32_32x32x16_bf16 v[100:115], v[180:183], v[168:171], v[100:115]
	v_mfma_f32_32x32x16_bf16 v[52:67], v[184:187], v[162:165], v[52:67]
	v_mfma_f32_32x32x16_bf16 v[116:131], v[184:187], v[168:171], v[116:131]
	s_waitcnt vmcnt(0) lgkmcnt(0)
	s_barrier
; #define MFMA32(a, b, c) __builtin_amdgcn_mfma_f32_32x32x16_bf16((a), (b), (c), 0, 0, 0)
; template <bool SWAP, class Epi>
; DI void gemm_tile(const u16* __restrict__ A, int lda, const u16* __restrict__ Bw, int ldb, int K, char* lds, Epi epi) {
;     ...
;   auto compute = [&](int st) {
;     const char* as = lds + st * GEMM_STAGE;
;     const char* bs = as + 36864;
; #pragma unroll
;     for (int ks = 0; ks < 4; ++ks) {
;       bf16x8 af[2], bfr[2];
; #pragma unroll
;       for (int mi = 0; mi < 2; ++mi) af[mi] = *(const bf16x8*)(as + ((wm * 64 + mi * 32 + r) * 72 + ks * 16 + 8 * h) * 2);
; #pragma unroll
;       for (int ni = 0; ni < 2; ++ni) bfr[ni] = *(const bf16x8*)(bs + ((wn * 64 + ni * 32 + r) * 72 + ks * 16 + 8 * h) * 2);
; #pragma unroll
;       for (int mi = 0; mi < 2; ++mi)
; #pragma unroll
;         for (int ni = 0; ni < 2; ++ni) {
;           if (SWAP) acc[mi][ni] = MFMA32(bfr[ni], af[mi], acc[mi][ni]);
;           else acc[mi][ni] = MFMA32(af[mi], bfr[ni], acc[mi][ni]);
;         }
;     }
;   };
;   gload(0, ra0, rb0);
;   lstore(0, ra0, rb0);
;   gload(1, ra1, rb1);
;   __syncthreads();
;   for (int kt = 0; kt < nk; kt += 2) {
;     if (kt + 2 < nk) gload(kt + 2, ra0, rb0);
;     compute(0);
;     lstore(1, ra1, rb1);
;     __syncthreads();
;     if (kt + 3 < nk) gload(kt + 3, ra1, rb1);
;     compute(1);
;     if (kt + 2 < nk) lstore(0, ra0, rb0);
;     __syncthreads();
	ds_read_b128 v[132:135], v210 offset:0
	ds_read_b128 v[136:139], v210 offset:4096
	ds_read_b128 v[140:143], v214 offset:0
	ds_read_b128 v[144:147], v214 offset:4096
	ds_read_b128 v[148:151], v214 offset:16384
	ds_read_b128 v[158:161], v214 offset:20480
	s_mov_b32 m0, s45
	s_nop 0
	global_load_lds_dwordx4 v208, s[68:69]
	global_load_lds_dwordx4 v209, s[70:71] offset:1024
	global_load_lds_dwordx4 v208, s[72:73] offset:2048
	global_load_lds_dwordx4 v209, s[74:75] offset:3072
	ds_read_b128 v[162:165], v211 offset:0
	ds_read_b128 v[168:171], v211 offset:4096
	ds_read_b128 v[172:175], v215 offset:0
	ds_read_b128 v[176:179], v215 offset:4096
	ds_read_b128 v[180:183], v215 offset:16384
	ds_read_b128 v[184:187], v215 offset:20480
	s_waitcnt lgkmcnt(6)
	v_mfma_f32_32x32x16_bf16 v[4:19], v[140:143], v[132:135], v[4:19]
	v_mfma_f32_32x32x16_bf16 v[68:83], v[140:143], v[136:139], v[68:83]
	v_mfma_f32_32x32x16_bf16 v[20:35], v[144:147], v[132:135], v[20:35]
	v_mfma_f32_32x32x16_bf16 v[84:99], v[144:147], v[136:139], v[84:99]
	v_mfma_f32_32x32x16_bf16 v[36:51], v[148:151], v[132:135], v[36:51]
	v_mfma_f32_32x32x16_bf16 v[100:115], v[148:151], v[136:139], v[100:115]
	v_mfma_f32_32x32x16_bf16 v[52:67], v[158:161], v[132:135], v[52:67]
	v_mfma_f32_32x32x16_bf16 v[116:131], v[158:161], v[136:139], v[116:131]
	s_mov_b32 m0, s47
	s_nop 0
	global_load_lds_dwordx4 v208, s[76:77]
	global_load_lds_dwordx4 v209, s[78:79] offset:1024
	global_load_lds_dwordx4 v208, s[80:81] offset:2048
	global_load_lds_dwordx4 v209, s[82:83] offset:3072
	v_add_u32_e32 v208, 0x80, v208
	v_add_u32_e32 v209, 0x80, v209
	ds_read_b128 v[132:135], v212 offset:0
	ds_read_b128 v[136:139], v212 offset:4096
	ds_read_b128 v[140:143], v216 offset:0
	ds_read_b128 v[144:147], v216 offset:4096
	ds_read_b128 v[148:151], v216 offset:16384
	ds_read_b128 v[158:161], v216 offset:20480
	s_waitcnt lgkmcnt(6)
	v_mfma_f32_32x32x16_bf16 v[4:19], v[172:175], v[162:165], v[4:19]
	v_mfma_f32_32x32x16_bf16 v[68:83], v[172:175], v[168:171], v[68:83]
	v_mfma_f32_32x32x16_bf16 v[20:35], v[176:179], v[162:165], v[20:35]
	v_mfma_f32_32x32x16_bf16 v[84:99], v[176:179], v[168:171], v[84:99]
	v_mfma_f32_32x32x16_bf16 v[36:51], v[180:183], v[162:165], v[36:51]
	v_mfma_f32_32x32x16_bf16 v[100:115], v[180:183], v[168:171], v[100:115]
	v_mfma_f32_32x32x16_bf16 v[52:67], v[184:187], v[162:165], v[52:67]
	v_mfma_f32_32x32x16_bf16 v[116:131], v[184:187], v[168:171], v[116:131]
	ds_read_b128 v[162:165], v213 offset:0
	ds_read_b128 v[168:171], v213 offset:4096
	ds_read_b128 v[172:175], v217 offset:0
	ds_read_b128 v[176:179], v217 offset:4096
	ds_read_b128 v[180:183], v217 offset:16384
	ds_read_b128 v[184:187], v217 offset:20480
	s_waitcnt lgkmcnt(6)
	v_mfma_f32_32x32x16_bf16 v[4:19], v[140:143], v[132:135], v[4:19]
	v_mfma_f32_32x32x16_bf16 v[68:83], v[140:143], v[136:139], v[68:83]
	v_mfma_f32_32x32x16_bf16 v[20:35], v[144:147], v[132:135], v[20:35]
	v_mfma_f32_32x32x16_bf16 v[84:99], v[144:147], v[136:139], v[84:99]
	v_mfma_f32_32x32x16_bf16 v[36:51], v[148:151], v[132:135], v[36:51]
	v_mfma_f32_32x32x16_bf16 v[100:115], v[148:151], v[136:139], v[100:115]
	v_mfma_f32_32x32x16_bf16 v[52:67], v[158:161], v[132:135], v[52:67]
	v_mfma_f32_32x32x16_bf16 v[116:131], v[158:161], v[136:139], v[116:131]
	s_waitcnt lgkmcnt(0)
	v_mfma_f32_32x32x16_bf16 v[4:19], v[172:175], v[162:165], v[4:19]
	v_mfma_f32_32x32x16_bf16 v[68:83], v[172:175], v[168:171], v[68:83]
	v_mfma_f32_32x32x16_bf16 v[20:35], v[176:179], v[162:165], v[20:35]
	v_mfma_f32_32x32x16_bf16 v[84:99], v[176:179], v[168:171], v[84:99]
	v_mfma_f32_32x32x16_bf16 v[36:51], v[180:183], v[162:165], v[36:51]
	v_mfma_f32_32x32x16_bf16 v[100:115], v[180:183], v[168:171], v[100:115]
	v_mfma_f32_32x32x16_bf16 v[52:67], v[184:187], v[162:165], v[52:67]
	v_mfma_f32_32x32x16_bf16 v[116:131], v[184:187], v[168:171], v[116:131]
	s_waitcnt vmcnt(0) lgkmcnt(0)
	s_barrier
	ds_read_b128 v[132:135], v210 offset:32768
	ds_read_b128 v[136:139], v210 offset:36864
	ds_read_b128 v[140:143], v214 offset:32768
	ds_read_b128 v[144:147], v214 offset:36864
	ds_read_b128 v[148:151], v214 offset:49152
	ds_read_b128 v[158:161], v214 offset:53248
	s_mov_b32 m0, s44
	s_nop 0
	global_load_lds_dwordx4 v208, s[68:69]
	global_load_lds_dwordx4 v209, s[70:71] offset:1024
	global_load_lds_dwordx4 v208, s[72:73] offset:2048
	global_load_lds_dwordx4 v209, s[74:75] offset:3072
	ds_read_b128 v[162:165], v211 offset:32768
	ds_read_b128 v[168:171], v211 offset:36864
	ds_read_b128 v[172:175], v215 offset:32768
	ds_read_b128 v[176:179], v215 offset:36864
	ds_read_b128 v[180:183], v215 offset:49152
	ds_read_b128 v[184:187], v215 offset:53248
	s_waitcnt lgkmcnt(6)
	v_mfma_f32_32x32x16_bf16 v[4:19], v[140:143], v[132:135], v[4:19]
	v_mfma_f32_32x32x16_bf16 v[68:83], v[140:143], v[136:139], v[68:83]
	v_mfma_f32_32x32x16_bf16 v[20:35], v[144:147], v[132:135], v[20:35]
	v_mfma_f32_32x32x16_bf16 v[84:99], v[144:147], v[136:139], v[84:99]
	v_mfma_f32_32x32x16_bf16 v[36:51], v[148:151], v[132:135], v[36:51]
	v_mfma_f32_32x32x16_bf16 v[100:115], v[148:151], v[136:139], v[100:115]
	v_mfma_f32_32x32x16_bf16 v[52:67], v[158:161], v[132:135], v[52:67]
	v_mfma_f32_32x32x16_bf16 v[116:131], v[158:161], v[136:139], v[116:131]
	s_mov_b32 m0, s46
	s_nop 0
	global_load_lds_dwordx4 v208, s[76:77]
	global_load_lds_dwordx4 v209, s[78:79] offset:1024
	global_load_lds_dwordx4 v208, s[80:81] offset:2048
	global_load_lds_dwordx4 v209, s[82:83] offset:3072
	v_add_u32_e32 v208, 0x80, v208
	v_add_u32_e32 v209, 0x80, v209
	ds_read_b128 v[132:135], v212 offset:32768
	ds_read_b128 v[136:139], v212 offset:36864
	ds_read_b128 v[140:143], v216 offset:32768
	ds_read_b128 v[144:147], v216 offset:36864
	ds_read_b128 v[148:151], v216 offset:49152
	ds_read_b128 v[158:161], v216 offset:53248
	s_waitcnt lgkmcnt(6)
; #define MFMA32(a, b, c) __builtin_amdgcn_mfma_f32_32x32x16_bf16((a), (b), (c), 0, 0, 0)
; template <bool SWAP, class Epi>
; DI void gemm_tile(const u16* __restrict__ A, int lda, const u16* __restrict__ Bw, int ldb, int K, char* lds, Epi epi) {
;     ...
;   auto compute = [&](int st) {
;     const char* as = lds + st * GEMM_STAGE;
;     const char* bs = as + 36864;
; #pragma unroll
;     for (int ks = 0; ks < 4; ++ks) {
;       bf16x8 af[2], bfr[2];
; #pragma unroll
;       for (int mi = 0; mi < 2; ++mi) af[mi] = *(const bf16x8*)(as + ((wm * 64 + mi * 32 + r) * 72 + ks * 16 + 8 * h) * 2);
; #pragma unroll
;       for (int ni = 0; ni < 2; ++ni) bfr[ni] = *(const bf16x8*)(bs + ((wn * 64 + ni * 32 + r) * 72 + ks * 16 + 8 * h) * 2);
; #pragma unroll
;       for (int mi = 0; mi < 2; ++mi)
; #pragma unroll
;         for (int ni = 0; ni < 2; ++ni) {
;           if (SWAP) acc[mi][ni] = MFMA32(bfr[ni], af[mi], acc[mi][ni]);
;           else acc[mi][ni] = MFMA32(af[mi], bfr[ni], acc[mi][ni]);
;         }
;     }
;   };
;   gload(0, ra0, rb0);
;   lstore(0, ra0, rb0);
;   gload(1, ra1, rb1);
;   __syncthreads();
;   for (int kt = 0; kt < nk; kt += 2) {
;     if (kt + 2 < nk) gload(kt + 2, ra0, rb0);
;     compute(0);
;     lstore(1, ra1, rb1);
;     __syncthreads();
;     if (kt + 3 < nk) gload(kt + 3, ra1, rb1);
;     compute(1);
;     if (kt + 2 < nk) lstore(0, ra0, rb0);
;     __syncthreads();
	v_mfma_f32_32x32x16_bf16 v[4:19], v[172:175], v[162:165], v[4:19]
	v_mfma_f32_32x32x16_bf16 v[68:83], v[172:175], v[168:171], v[68:83]
	v_mfma_f32_32x32x16_bf16 v[20:35], v[176:179], v[162:165], v[20:35]
	v_mfma_f32_32x32x16_bf16 v[84:99], v[176:179], v[168:171], v[84:99]
	v_mfma_f32_32x32x16_bf16 v[36:51], v[180:183], v[162:165], v[36:51]
	v_mfma_f32_32x32x16_bf16 v[100:115], v[180:183], v[168:171], v[100:115]
	v_mfma_f32_32x32x16_bf16 v[52:67], v[184:187], v[162:165], v[52:67]
	v_mfma_f32_32x32x16_bf16 v[116:131], v[184:187], v[168:171], v[116:131]
	ds_read_b128 v[162:165], v213 offset:32768
	ds_read_b128 v[168:171], v213 offset:36864
	ds_read_b128 v[172:175], v217 offset:32768
	ds_read_b128 v[176:179], v217 offset:36864
	ds_read_b128 v[180:183], v217 offset:49152
	ds_read_b128 v[184:187], v217 offset:53248
	s_waitcnt lgkmcnt(6)
	v_mfma_f32_32x32x16_bf16 v[4:19], v[140:143], v[132:135], v[4:19]
	v_mfma_f32_32x32x16_bf16 v[68:83], v[140:143], v[136:139], v[68:83]
	v_mfma_f32_32x32x16_bf16 v[20:35], v[144:147], v[132:135], v[20:35]
	v_mfma_f32_32x32x16_bf16 v[84:99], v[144:147], v[136:139], v[84:99]
	v_mfma_f32_32x32x16_bf16 v[36:51], v[148:151], v[132:135], v[36:51]
	v_mfma_f32_32x32x16_bf16 v[100:115], v[148:151], v[136:139], v[100:115]
	v_mfma_f32_32x32x16_bf16 v[52:67], v[158:161], v[132:135], v[52:67]
	v_mfma_f32_32x32x16_bf16 v[116:131], v[158:161], v[136:139], v[116:131]
	s_waitcnt lgkmcnt(0)
	v_mfma_f32_32x32x16_bf16 v[4:19], v[172:175], v[162:165], v[4:19]
	v_mfma_f32_32x32x16_bf16 v[68:83], v[172:175], v[168:171], v[68:83]
	v_mfma_f32_32x32x16_bf16 v[20:35], v[176:179], v[162:165], v[20:35]
	v_mfma_f32_32x32x16_bf16 v[84:99], v[176:179], v[168:171], v[84:99]
	v_mfma_f32_32x32x16_bf16 v[36:51], v[180:183], v[162:165], v[36:51]
	v_mfma_f32_32x32x16_bf16 v[100:115], v[180:183], v[168:171], v[100:115]
	v_mfma_f32_32x32x16_bf16 v[52:67], v[184:187], v[162:165], v[52:67]
	v_mfma_f32_32x32x16_bf16 v[116:131], v[184:187], v[168:171], v[116:131]
	s_waitcnt vmcnt(0) lgkmcnt(0)
	s_barrier
	ds_read_b128 v[132:135], v210 offset:0
	ds_read_b128 v[136:139], v210 offset:4096
	ds_read_b128 v[140:143], v214 offset:0
	ds_read_b128 v[144:147], v214 offset:4096
	ds_read_b128 v[148:151], v214 offset:16384
	ds_read_b128 v[158:161], v214 offset:20480
	s_mov_b32 m0, s45
	s_nop 0
	global_load_lds_dwordx4 v208, s[68:69]
	global_load_lds_dwordx4 v209, s[70:71] offset:1024
	global_load_lds_dwordx4 v208, s[72:73] offset:2048
	global_load_lds_dwordx4 v209, s[74:75] offset:3072
	ds_read_b128 v[162:165], v211 offset:0
	ds_read_b128 v[168:171], v211 offset:4096
	ds_read_b128 v[172:175], v215 offset:0
	ds_read_b128 v[176:179], v215 offset:4096
	ds_read_b128 v[180:183], v215 offset:16384
	ds_read_b128 v[184:187], v215 offset:20480
	s_waitcnt lgkmcnt(6)
	v_mfma_f32_32x32x16_bf16 v[4:19], v[140:143], v[132:135], v[4:19]
	v_mfma_f32_32x32x16_bf16 v[68:83], v[140:143], v[136:139], v[68:83]
	v_mfma_f32_32x32x16_bf16 v[20:35], v[144:147], v[132:135], v[20:35]
	v_mfma_f32_32x32x16_bf16 v[84:99], v[144:147], v[136:139], v[84:99]
	v_mfma_f32_32x32x16_bf16 v[36:51], v[148:151], v[132:135], v[36:51]
	v_mfma_f32_32x32x16_bf16 v[100:115], v[148:151], v[136:139], v[100:115]
	v_mfma_f32_32x32x16_bf16 v[52:67], v[158:161], v[132:135], v[52:67]
	v_mfma_f32_32x32x16_bf16 v[116:131], v[158:161], v[136:139], v[116:131]
	s_mov_b32 m0, s47
	s_nop 0
	global_load_lds_dwordx4 v208, s[76:77]
	global_load_lds_dwordx4 v209, s[78:79] offset:1024
	global_load_lds_dwordx4 v208, s[80:81] offset:2048
	global_load_lds_dwordx4 v209, s[82:83] offset:3072
	v_add_u32_e32 v208, 0x80, v208
	v_add_u32_e32 v209, 0x80, v209
	ds_read_b128 v[132:135], v212 offset:0
	ds_read_b128 v[136:139], v212 offset:4096
	ds_read_b128 v[140:143], v216 offset:0
	ds_read_b128 v[144:147], v216 offset:4096
	ds_read_b128 v[148:151], v216 offset:16384
	ds_read_b128 v[158:161], v216 offset:20480
	s_waitcnt lgkmcnt(6)
	v_mfma_f32_32x32x16_bf16 v[4:19], v[172:175], v[162:165], v[4:19]
	v_mfma_f32_32x32x16_bf16 v[68:83], v[172:175], v[168:171], v[68:83]
	v_mfma_f32_32x32x16_bf16 v[20:35], v[176:179], v[162:165], v[20:35]
	v_mfma_f32_32x32x16_bf16 v[84:99], v[176:179], v[168:171], v[84:99]
	v_mfma_f32_32x32x16_bf16 v[36:51], v[180:183], v[162:165], v[36:51]
	v_mfma_f32_32x32x16_bf16 v[100:115], v[180:183], v[168:171], v[100:115]
	v_mfma_f32_32x32x16_bf16 v[52:67], v[184:187], v[162:165], v[52:67]
	v_mfma_f32_32x32x16_bf16 v[116:131], v[184:187], v[168:171], v[116:131]
	ds_read_b128 v[162:165], v213 offset:0
	ds_read_b128 v[168:171], v213 offset:4096
	ds_read_b128 v[172:175], v217 offset:0
	ds_read_b128 v[176:179], v217 offset:4096
	ds_read_b128 v[180:183], v217 offset:16384
	ds_read_b128 v[184:187], v217 offset:20480
	s_waitcnt lgkmcnt(6)
	v_mfma_f32_32x32x16_bf16 v[4:19], v[140:143], v[132:135], v[4:19]
	v_mfma_f32_32x32x16_bf16 v[68:83], v[140:143], v[136:139], v[68:83]
	v_mfma_f32_32x32x16_bf16 v[20:35], v[144:147], v[132:135], v[20:35]
	v_mfma_f32_32x32x16_bf16 v[84:99], v[144:147], v[136:139], v[84:99]
	v_mfma_f32_32x32x16_bf16 v[36:51], v[148:151], v[132:135], v[36:51]
	v_mfma_f32_32x32x16_bf16 v[100:115], v[148:151], v[136:139], v[100:115]
	v_mfma_f32_32x32x16_bf16 v[52:67], v[158:161], v[132:135], v[52:67]
	v_mfma_f32_32x32x16_bf16 v[116:131], v[158:161], v[136:139], v[116:131]
	s_waitcnt lgkmcnt(0)
	v_mfma_f32_32x32x16_bf16 v[4:19], v[172:175], v[162:165], v[4:19]
	v_mfma_f32_32x32x16_bf16 v[68:83], v[172:175], v[168:171], v[68:83]
	v_mfma_f32_32x32x16_bf16 v[20:35], v[176:179], v[162:165], v[20:35]
	v_mfma_f32_32x32x16_bf16 v[84:99], v[176:179], v[168:171], v[84:99]
	v_mfma_f32_32x32x16_bf16 v[36:51], v[180:183], v[162:165], v[36:51]
	v_mfma_f32_32x32x16_bf16 v[100:115], v[180:183], v[168:171], v[100:115]
	v_mfma_f32_32x32x16_bf16 v[52:67], v[184:187], v[162:165], v[52:67]
	v_mfma_f32_32x32x16_bf16 v[116:131], v[184:187], v[168:171], v[116:131]
	s_waitcnt vmcnt(0) lgkmcnt(0)
	s_barrier
; #define MFMA32(a, b, c) __builtin_amdgcn_mfma_f32_32x32x16_bf16((a), (b), (c), 0, 0, 0)
; template <bool SWAP, class Epi>
; DI void gemm_tile(const u16* __restrict__ A, int lda, const u16* __restrict__ Bw, int ldb, int K, char* lds, Epi epi) {
;     ...
;   auto compute = [&](int st) {
;     const char* as = lds + st * GEMM_STAGE;
;     const char* bs = as + 36864;
; #pragma unroll
;     for (int ks = 0; ks < 4; ++ks) {
;       bf16x8 af[2], bfr[2];
; #pragma unroll
;       for (int mi = 0; mi < 2; ++mi) af[mi] = *(const bf16x8*)(as + ((wm * 64 + mi * 32 + r) * 72 + ks * 16 + 8 * h) * 2);
; #pragma unroll
;       for (int ni = 0; ni < 2; ++ni) bfr[ni] = *(const bf16x8*)(bs + ((wn * 64 + ni * 32 + r) * 72 + ks * 16 + 8 * h) * 2);
; #pragma unroll
;       for (int mi = 0; mi < 2; ++mi)
; #pragma unroll
;         for (int ni = 0; ni < 2; ++ni) {
;           if (SWAP) acc[mi][ni] = MFMA32(bfr[ni], af[mi], acc[mi][ni]);
;           else acc[mi][ni] = MFMA32(af[mi], bfr[ni], acc[mi][ni]);
;         }
;     }
;   };
;   gload(0, ra0, rb0);
;   lstore(0, ra0, rb0);
;   gload(1, ra1, rb1);
;   __syncthreads();
;   for (int kt = 0; kt < nk; kt += 2) {
;     if (kt + 2 < nk) gload(kt + 2, ra0, rb0);
;     compute(0);
;     lstore(1, ra1, rb1);
;     __syncthreads();
;     if (kt + 3 < nk) gload(kt + 3, ra1, rb1);
;     compute(1);
;     if (kt + 2 < nk) lstore(0, ra0, rb0);
;     __syncthreads();
	ds_read_b128 v[132:135], v210 offset:32768
	ds_read_b128 v[136:139], v210 offset:36864
	ds_read_b128 v[140:143], v214 offset:32768
	ds_read_b128 v[144:147], v214 offset:36864
	ds_read_b128 v[148:151], v214 offset:49152
	ds_read_b128 v[158:161], v214 offset:53248
	s_mov_b32 m0, s44
	s_nop 0
	global_load_lds_dwordx4 v208, s[68:69]
	global_load_lds_dwordx4 v209, s[70:71] offset:1024
	global_load_lds_dwordx4 v208, s[72:73] offset:2048
	global_load_lds_dwordx4 v209, s[74:75] offset:3072
	ds_read_b128 v[162:165], v211 offset:32768
	ds_read_b128 v[168:171], v211 offset:36864
	ds_read_b128 v[172:175], v215 offset:32768
	ds_read_b128 v[176:179], v215 offset:36864
	ds_read_b128 v[180:183], v215 offset:49152
	ds_read_b128 v[184:187], v215 offset:53248
	s_waitcnt lgkmcnt(6)
	v_mfma_f32_32x32x16_bf16 v[4:19], v[140:143], v[132:135], v[4:19]
	v_mfma_f32_32x32x16_bf16 v[68:83], v[140:143], v[136:139], v[68:83]
	v_mfma_f32_32x32x16_bf16 v[20:35], v[144:147], v[132:135], v[20:35]
	v_mfma_f32_32x32x16_bf16 v[84:99], v[144:147], v[136:139], v[84:99]
	v_mfma_f32_32x32x16_bf16 v[36:51], v[148:151], v[132:135], v[36:51]
	v_mfma_f32_32x32x16_bf16 v[100:115], v[148:151], v[136:139], v[100:115]
	v_mfma_f32_32x32x16_bf16 v[52:67], v[158:161], v[132:135], v[52:67]
	v_mfma_f32_32x32x16_bf16 v[116:131], v[158:161], v[136:139], v[116:131]
	s_mov_b32 m0, s46
	s_nop 0
	global_load_lds_dwordx4 v208, s[76:77]
	global_load_lds_dwordx4 v209, s[78:79] offset:1024
	global_load_lds_dwordx4 v208, s[80:81] offset:2048
	global_load_lds_dwordx4 v209, s[82:83] offset:3072
	v_add_u32_e32 v208, 0x80, v208
	v_add_u32_e32 v209, 0x80, v209
	ds_read_b128 v[132:135], v212 offset:32768
	ds_read_b128 v[136:139], v212 offset:36864
	ds_read_b128 v[140:143], v216 offset:32768
	ds_read_b128 v[144:147], v216 offset:36864
	ds_read_b128 v[148:151], v216 offset:49152
	ds_read_b128 v[158:161], v216 offset:53248
	s_waitcnt lgkmcnt(6)
	v_mfma_f32_32x32x16_bf16 v[4:19], v[172:175], v[162:165], v[4:19]
	v_mfma_f32_32x32x16_bf16 v[68:83], v[172:175], v[168:171], v[68:83]
	v_mfma_f32_32x32x16_bf16 v[20:35], v[176:179], v[162:165], v[20:35]
	v_mfma_f32_32x32x16_bf16 v[84:99], v[176:179], v[168:171], v[84:99]
	v_mfma_f32_32x32x16_bf16 v[36:51], v[180:183], v[162:165], v[36:51]
	v_mfma_f32_32x32x16_bf16 v[100:115], v[180:183], v[168:171], v[100:115]
	v_mfma_f32_32x32x16_bf16 v[52:67], v[184:187], v[162:165], v[52:67]
	v_mfma_f32_32x32x16_bf16 v[116:131], v[184:187], v[168:171], v[116:131]
	ds_read_b128 v[162:165], v213 offset:32768
	ds_read_b128 v[168:171], v213 offset:36864
	ds_read_b128 v[172:175], v217 offset:32768
	ds_read_b128 v[176:179], v217 offset:36864
	ds_read_b128 v[180:183], v217 offset:49152
	ds_read_b128 v[184:187], v217 offset:53248
	s_waitcnt lgkmcnt(6)
	v_mfma_f32_32x32x16_bf16 v[4:19], v[140:143], v[132:135], v[4:19]
	v_mfma_f32_32x32x16_bf16 v[68:83], v[140:143], v[136:139], v[68:83]
	v_mfma_f32_32x32x16_bf16 v[20:35], v[144:147], v[132:135], v[20:35]
	v_mfma_f32_32x32x16_bf16 v[84:99], v[144:147], v[136:139], v[84:99]
	v_mfma_f32_32x32x16_bf16 v[36:51], v[148:151], v[132:135], v[36:51]
	v_mfma_f32_32x32x16_bf16 v[100:115], v[148:151], v[136:139], v[100:115]
	v_mfma_f32_32x32x16_bf16 v[52:67], v[158:161], v[132:135], v[52:67]
	v_mfma_f32_32x32x16_bf16 v[116:131], v[158:161], v[136:139], v[116:131]
	s_waitcnt lgkmcnt(0)
	v_mfma_f32_32x32x16_bf16 v[4:19], v[172:175], v[162:165], v[4:19]
	v_mfma_f32_32x32x16_bf16 v[68:83], v[172:175], v[168:171], v[68:83]
	v_mfma_f32_32x32x16_bf16 v[20:35], v[176:179], v[162:165], v[20:35]
	v_mfma_f32_32x32x16_bf16 v[84:99], v[176:179], v[168:171], v[84:99]
	v_mfma_f32_32x32x16_bf16 v[36:51], v[180:183], v[162:165], v[36:51]
	v_mfma_f32_32x32x16_bf16 v[100:115], v[180:183], v[168:171], v[100:115]
	v_mfma_f32_32x32x16_bf16 v[52:67], v[184:187], v[162:165], v[52:67]
	v_mfma_f32_32x32x16_bf16 v[116:131], v[184:187], v[168:171], v[116:131]
	s_waitcnt vmcnt(0) lgkmcnt(0)
	s_barrier
	ds_read_b128 v[132:135], v210 offset:0
	ds_read_b128 v[136:139], v210 offset:4096
	ds_read_b128 v[140:143], v214 offset:0
	ds_read_b128 v[144:147], v214 offset:4096
	ds_read_b128 v[148:151], v214 offset:16384
	ds_read_b128 v[158:161], v214 offset:20480
	s_mov_b32 m0, s45
	s_nop 0
	global_load_lds_dwordx4 v208, s[68:69]
	global_load_lds_dwordx4 v209, s[70:71] offset:1024
	global_load_lds_dwordx4 v208, s[72:73] offset:2048
	global_load_lds_dwordx4 v209, s[74:75] offset:3072
	ds_read_b128 v[162:165], v211 offset:0
	ds_read_b128 v[168:171], v211 offset:4096
	ds_read_b128 v[172:175], v215 offset:0
	ds_read_b128 v[176:179], v215 offset:4096
	ds_read_b128 v[180:183], v215 offset:16384
	ds_read_b128 v[184:187], v215 offset:20480
	s_waitcnt lgkmcnt(6)
	v_mfma_f32_32x32x16_bf16 v[4:19], v[140:143], v[132:135], v[4:19]
	v_mfma_f32_32x32x16_bf16 v[68:83], v[140:143], v[136:139], v[68:83]
	v_mfma_f32_32x32x16_bf16 v[20:35], v[144:147], v[132:135], v[20:35]
	v_mfma_f32_32x32x16_bf16 v[84:99], v[144:147], v[136:139], v[84:99]
	v_mfma_f32_32x32x16_bf16 v[36:51], v[148:151], v[132:135], v[36:51]
	v_mfma_f32_32x32x16_bf16 v[100:115], v[148:151], v[136:139], v[100:115]
	v_mfma_f32_32x32x16_bf16 v[52:67], v[158:161], v[132:135], v[52:67]
	v_mfma_f32_32x32x16_bf16 v[116:131], v[158:161], v[136:139], v[116:131]
	s_mov_b32 m0, s47
	s_nop 0
	global_load_lds_dwordx4 v208, s[76:77]
	global_load_lds_dwordx4 v209, s[78:79] offset:1024
	global_load_lds_dwordx4 v208, s[80:81] offset:2048
	global_load_lds_dwordx4 v209, s[82:83] offset:3072
	v_add_u32_e32 v208, 0x80, v208
	v_add_u32_e32 v209, 0x80, v209
	ds_read_b128 v[132:135], v212 offset:0
	ds_read_b128 v[136:139], v212 offset:4096
	ds_read_b128 v[140:143], v216 offset:0
	ds_read_b128 v[144:147], v216 offset:4096
	ds_read_b128 v[148:151], v216 offset:16384
	ds_read_b128 v[158:161], v216 offset:20480
	s_waitcnt lgkmcnt(6)
; #define MFMA32(a, b, c) __builtin_amdgcn_mfma_f32_32x32x16_bf16((a), (b), (c), 0, 0, 0)
; template <bool SWAP, class Epi>
; DI void gemm_tile(const u16* __restrict__ A, int lda, const u16* __restrict__ Bw, int ldb, int K, char* lds, Epi epi) {
;     ...
;   auto compute = [&](int st) {
;     const char* as = lds + st * GEMM_STAGE;
;     const char* bs = as + 36864;
; #pragma unroll
;     for (int ks = 0; ks < 4; ++ks) {
;       bf16x8 af[2], bfr[2];
; #pragma unroll
;       for (int mi = 0; mi < 2; ++mi) af[mi] = *(const bf16x8*)(as + ((wm * 64 + mi * 32 + r) * 72 + ks * 16 + 8 * h) * 2);
; #pragma unroll
;       for (int ni = 0; ni < 2; ++ni) bfr[ni] = *(const bf16x8*)(bs + ((wn * 64 + ni * 32 + r) * 72 + ks * 16 + 8 * h) * 2);
; #pragma unroll
;       for (int mi = 0; mi < 2; ++mi)
; #pragma unroll
;         for (int ni = 0; ni < 2; ++ni) {
;           if (SWAP) acc[mi][ni] = MFMA32(bfr[ni], af[mi], acc[mi][ni]);
;           else acc[mi][ni] = MFMA32(af[mi], bfr[ni], acc[mi][ni]);
;         }
;     }
;   };
;   gload(0, ra0, rb0);
;   lstore(0, ra0, rb0);
;   gload(1, ra1, rb1);
;   __syncthreads();
;   for (int kt = 0; kt < nk; kt += 2) {
;     if (kt + 2 < nk) gload(kt + 2, ra0, rb0);
;     compute(0);
;     lstore(1, ra1, rb1);
;     __syncthreads();
;     if (kt + 3 < nk) gload(kt + 3, ra1, rb1);
;     compute(1);
;     if (kt + 2 < nk) lstore(0, ra0, rb0);
;     __syncthreads();
	v_mfma_f32_32x32x16_bf16 v[4:19], v[172:175], v[162:165], v[4:19]
	v_mfma_f32_32x32x16_bf16 v[68:83], v[172:175], v[168:171], v[68:83]
	v_mfma_f32_32x32x16_bf16 v[20:35], v[176:179], v[162:165], v[20:35]
	v_mfma_f32_32x32x16_bf16 v[84:99], v[176:179], v[168:171], v[84:99]
	v_mfma_f32_32x32x16_bf16 v[36:51], v[180:183], v[162:165], v[36:51]
	v_mfma_f32_32x32x16_bf16 v[100:115], v[180:183], v[168:171], v[100:115]
	v_mfma_f32_32x32x16_bf16 v[52:67], v[184:187], v[162:165], v[52:67]
	v_mfma_f32_32x32x16_bf16 v[116:131], v[184:187], v[168:171], v[116:131]
	ds_read_b128 v[162:165], v213 offset:0
	ds_read_b128 v[168:171], v213 offset:4096
	ds_read_b128 v[172:175], v217 offset:0
	ds_read_b128 v[176:179], v217 offset:4096
	ds_read_b128 v[180:183], v217 offset:16384
	ds_read_b128 v[184:187], v217 offset:20480
	s_waitcnt lgkmcnt(6)
	v_mfma_f32_32x32x16_bf16 v[4:19], v[140:143], v[132:135], v[4:19]
	v_mfma_f32_32x32x16_bf16 v[68:83], v[140:143], v[136:139], v[68:83]
	v_mfma_f32_32x32x16_bf16 v[20:35], v[144:147], v[132:135], v[20:35]
	v_mfma_f32_32x32x16_bf16 v[84:99], v[144:147], v[136:139], v[84:99]
	v_mfma_f32_32x32x16_bf16 v[36:51], v[148:151], v[132:135], v[36:51]
	v_mfma_f32_32x32x16_bf16 v[100:115], v[148:151], v[136:139], v[100:115]
	v_mfma_f32_32x32x16_bf16 v[52:67], v[158:161], v[132:135], v[52:67]
	v_mfma_f32_32x32x16_bf16 v[116:131], v[158:161], v[136:139], v[116:131]
	s_waitcnt lgkmcnt(0)
	v_mfma_f32_32x32x16_bf16 v[4:19], v[172:175], v[162:165], v[4:19]
	v_mfma_f32_32x32x16_bf16 v[68:83], v[172:175], v[168:171], v[68:83]
	v_mfma_f32_32x32x16_bf16 v[20:35], v[176:179], v[162:165], v[20:35]
	v_mfma_f32_32x32x16_bf16 v[84:99], v[176:179], v[168:171], v[84:99]
	v_mfma_f32_32x32x16_bf16 v[36:51], v[180:183], v[162:165], v[36:51]
	v_mfma_f32_32x32x16_bf16 v[100:115], v[180:183], v[168:171], v[100:115]
	v_mfma_f32_32x32x16_bf16 v[52:67], v[184:187], v[162:165], v[52:67]
	v_mfma_f32_32x32x16_bf16 v[116:131], v[184:187], v[168:171], v[116:131]
	s_waitcnt vmcnt(0) lgkmcnt(0)
	s_barrier
	ds_read_b128 v[132:135], v210 offset:32768
	ds_read_b128 v[136:139], v210 offset:36864
	ds_read_b128 v[140:143], v214 offset:32768
	ds_read_b128 v[144:147], v214 offset:36864
	ds_read_b128 v[148:151], v214 offset:49152
	ds_read_b128 v[158:161], v214 offset:53248
	s_mov_b32 m0, s44
	s_nop 0
	global_load_lds_dwordx4 v208, s[68:69]
	global_load_lds_dwordx4 v209, s[70:71] offset:1024
	global_load_lds_dwordx4 v208, s[72:73] offset:2048
	global_load_lds_dwordx4 v209, s[74:75] offset:3072
	ds_read_b128 v[162:165], v211 offset:32768
	ds_read_b128 v[168:171], v211 offset:36864
	ds_read_b128 v[172:175], v215 offset:32768
	ds_read_b128 v[176:179], v215 offset:36864
	ds_read_b128 v[180:183], v215 offset:49152
	ds_read_b128 v[184:187], v215 offset:53248
	s_waitcnt lgkmcnt(6)
	v_mfma_f32_32x32x16_bf16 v[4:19], v[140:143], v[132:135], v[4:19]
	v_mfma_f32_32x32x16_bf16 v[68:83], v[140:143], v[136:139], v[68:83]
	v_mfma_f32_32x32x16_bf16 v[20:35], v[144:147], v[132:135], v[20:35]
	v_mfma_f32_32x32x16_bf16 v[84:99], v[144:147], v[136:139], v[84:99]
	v_mfma_f32_32x32x16_bf16 v[36:51], v[148:151], v[132:135], v[36:51]
	v_mfma_f32_32x32x16_bf16 v[100:115], v[148:151], v[136:139], v[100:115]
	v_mfma_f32_32x32x16_bf16 v[52:67], v[158:161], v[132:135], v[52:67]
	v_mfma_f32_32x32x16_bf16 v[116:131], v[158:161], v[136:139], v[116:131]
	s_mov_b32 m0, s46
	s_nop 0
	global_load_lds_dwordx4 v208, s[76:77]
	global_load_lds_dwordx4 v209, s[78:79] offset:1024
	global_load_lds_dwordx4 v208, s[80:81] offset:2048
	global_load_lds_dwordx4 v209, s[82:83] offset:3072
	v_add_u32_e32 v208, 0x80, v208
	v_add_u32_e32 v209, 0x80, v209
	ds_read_b128 v[132:135], v212 offset:32768
	ds_read_b128 v[136:139], v212 offset:36864
	ds_read_b128 v[140:143], v216 offset:32768
	ds_read_b128 v[144:147], v216 offset:36864
	ds_read_b128 v[148:151], v216 offset:49152
	ds_read_b128 v[158:161], v216 offset:53248
	s_waitcnt lgkmcnt(6)
	v_mfma_f32_32x32x16_bf16 v[4:19], v[172:175], v[162:165], v[4:19]
	v_mfma_f32_32x32x16_bf16 v[68:83], v[172:175], v[168:171], v[68:83]
	v_mfma_f32_32x32x16_bf16 v[20:35], v[176:179], v[162:165], v[20:35]
	v_mfma_f32_32x32x16_bf16 v[84:99], v[176:179], v[168:171], v[84:99]
	v_mfma_f32_32x32x16_bf16 v[36:51], v[180:183], v[162:165], v[36:51]
	v_mfma_f32_32x32x16_bf16 v[100:115], v[180:183], v[168:171], v[100:115]
	v_mfma_f32_32x32x16_bf16 v[52:67], v[184:187], v[162:165], v[52:67]
	v_mfma_f32_32x32x16_bf16 v[116:131], v[184:187], v[168:171], v[116:131]
	ds_read_b128 v[162:165], v213 offset:32768
	ds_read_b128 v[168:171], v213 offset:36864
	ds_read_b128 v[172:175], v217 offset:32768
	ds_read_b128 v[176:179], v217 offset:36864
	ds_read_b128 v[180:183], v217 offset:49152
	ds_read_b128 v[184:187], v217 offset:53248
	s_waitcnt lgkmcnt(6)
	v_mfma_f32_32x32x16_bf16 v[4:19], v[140:143], v[132:135], v[4:19]
	v_mfma_f32_32x32x16_bf16 v[68:83], v[140:143], v[136:139], v[68:83]
	v_mfma_f32_32x32x16_bf16 v[20:35], v[144:147], v[132:135], v[20:35]
	v_mfma_f32_32x32x16_bf16 v[84:99], v[144:147], v[136:139], v[84:99]
	v_mfma_f32_32x32x16_bf16 v[36:51], v[148:151], v[132:135], v[36:51]
	v_mfma_f32_32x32x16_bf16 v[100:115], v[148:151], v[136:139], v[100:115]
	v_mfma_f32_32x32x16_bf16 v[52:67], v[158:161], v[132:135], v[52:67]
	v_mfma_f32_32x32x16_bf16 v[116:131], v[158:161], v[136:139], v[116:131]
	s_waitcnt lgkmcnt(0)
	v_mfma_f32_32x32x16_bf16 v[4:19], v[172:175], v[162:165], v[4:19]
	v_mfma_f32_32x32x16_bf16 v[68:83], v[172:175], v[168:171], v[68:83]
	v_mfma_f32_32x32x16_bf16 v[20:35], v[176:179], v[162:165], v[20:35]
	v_mfma_f32_32x32x16_bf16 v[84:99], v[176:179], v[168:171], v[84:99]
	v_mfma_f32_32x32x16_bf16 v[36:51], v[180:183], v[162:165], v[36:51]
	v_mfma_f32_32x32x16_bf16 v[100:115], v[180:183], v[168:171], v[100:115]
	v_mfma_f32_32x32x16_bf16 v[52:67], v[184:187], v[162:165], v[52:67]
	v_mfma_f32_32x32x16_bf16 v[116:131], v[184:187], v[168:171], v[116:131]
	s_waitcnt vmcnt(0) lgkmcnt(0)
	s_barrier
; #define MFMA32(a, b, c) __builtin_amdgcn_mfma_f32_32x32x16_bf16((a), (b), (c), 0, 0, 0)
; template <bool SWAP, class Epi>
; DI void gemm_tile(const u16* __restrict__ A, int lda, const u16* __restrict__ Bw, int ldb, int K, char* lds, Epi epi) {
;     ...
;   auto compute = [&](int st) {
;     const char* as = lds + st * GEMM_STAGE;
;     const char* bs = as + 36864;
; #pragma unroll
;     for (int ks = 0; ks < 4; ++ks) {
;       bf16x8 af[2], bfr[2];
; #pragma unroll
;       for (int mi = 0; mi < 2; ++mi) af[mi] = *(const bf16x8*)(as + ((wm * 64 + mi * 32 + r) * 72 + ks * 16 + 8 * h) * 2);
; #pragma unroll
;       for (int ni = 0; ni < 2; ++ni) bfr[ni] = *(const bf16x8*)(bs + ((wn * 64 + ni * 32 + r) * 72 + ks * 16 + 8 * h) * 2);
; #pragma unroll
;       for (int mi = 0; mi < 2; ++mi)
; #pragma unroll
;         for (int ni = 0; ni < 2; ++ni) {
;           if (SWAP) acc[mi][ni] = MFMA32(bfr[ni], af[mi], acc[mi][ni]);
;           else acc[mi][ni] = MFMA32(af[mi], bfr[ni], acc[mi][ni]);
;         }
;     }
;   };
;   gload(0, ra0, rb0);
;   lstore(0, ra0, rb0);
;   gload(1, ra1, rb1);
;   __syncthreads();
;   for (int kt = 0; kt < nk; kt += 2) {
;     if (kt + 2 < nk) gload(kt + 2, ra0, rb0);
;     compute(0);
;     lstore(1, ra1, rb1);
;     __syncthreads();
;     if (kt + 3 < nk) gload(kt + 3, ra1, rb1);
;     compute(1);
;     if (kt + 2 < nk) lstore(0, ra0, rb0);
;     __syncthreads();
	ds_read_b128 v[132:135], v210 offset:0
	ds_read_b128 v[136:139], v210 offset:4096
	ds_read_b128 v[140:143], v214 offset:0
	ds_read_b128 v[144:147], v214 offset:4096
	ds_read_b128 v[148:151], v214 offset:16384
	ds_read_b128 v[158:161], v214 offset:20480
	s_mov_b32 m0, s45
	s_nop 0
	global_load_lds_dwordx4 v208, s[68:69]
	global_load_lds_dwordx4 v209, s[70:71] offset:1024
	global_load_lds_dwordx4 v208, s[72:73] offset:2048
	global_load_lds_dwordx4 v209, s[74:75] offset:3072
	ds_read_b128 v[162:165], v211 offset:0
	ds_read_b128 v[168:171], v211 offset:4096
	ds_read_b128 v[172:175], v215 offset:0
	ds_read_b128 v[176:179], v215 offset:4096
	ds_read_b128 v[180:183], v215 offset:16384
	ds_read_b128 v[184:187], v215 offset:20480
	s_waitcnt lgkmcnt(6)
	v_mfma_f32_32x32x16_bf16 v[4:19], v[140:143], v[132:135], v[4:19]
	v_mfma_f32_32x32x16_bf16 v[68:83], v[140:143], v[136:139], v[68:83]
	v_mfma_f32_32x32x16_bf16 v[20:35], v[144:147], v[132:135], v[20:35]
	v_mfma_f32_32x32x16_bf16 v[84:99], v[144:147], v[136:139], v[84:99]
	v_mfma_f32_32x32x16_bf16 v[36:51], v[148:151], v[132:135], v[36:51]
	v_mfma_f32_32x32x16_bf16 v[100:115], v[148:151], v[136:139], v[100:115]
	v_mfma_f32_32x32x16_bf16 v[52:67], v[158:161], v[132:135], v[52:67]
	v_mfma_f32_32x32x16_bf16 v[116:131], v[158:161], v[136:139], v[116:131]
	s_mov_b32 m0, s47
	s_nop 0
	global_load_lds_dwordx4 v208, s[76:77]
	global_load_lds_dwordx4 v209, s[78:79] offset:1024
	global_load_lds_dwordx4 v208, s[80:81] offset:2048
	global_load_lds_dwordx4 v209, s[82:83] offset:3072
	v_add_u32_e32 v208, 0x80, v208
	v_add_u32_e32 v209, 0x80, v209
	ds_read_b128 v[132:135], v212 offset:0
	ds_read_b128 v[136:139], v212 offset:4096
	ds_read_b128 v[140:143], v216 offset:0
	ds_read_b128 v[144:147], v216 offset:4096
	ds_read_b128 v[148:151], v216 offset:16384
	ds_read_b128 v[158:161], v216 offset:20480
	s_waitcnt lgkmcnt(6)
	v_mfma_f32_32x32x16_bf16 v[4:19], v[172:175], v[162:165], v[4:19]
	v_mfma_f32_32x32x16_bf16 v[68:83], v[172:175], v[168:171], v[68:83]
	v_mfma_f32_32x32x16_bf16 v[20:35], v[176:179], v[162:165], v[20:35]
	v_mfma_f32_32x32x16_bf16 v[84:99], v[176:179], v[168:171], v[84:99]
	v_mfma_f32_32x32x16_bf16 v[36:51], v[180:183], v[162:165], v[36:51]
	v_mfma_f32_32x32x16_bf16 v[100:115], v[180:183], v[168:171], v[100:115]
	v_mfma_f32_32x32x16_bf16 v[52:67], v[184:187], v[162:165], v[52:67]
	v_mfma_f32_32x32x16_bf16 v[116:131], v[184:187], v[168:171], v[116:131]
	ds_read_b128 v[162:165], v213 offset:0
	ds_read_b128 v[168:171], v213 offset:4096
	ds_read_b128 v[172:175], v217 offset:0
	ds_read_b128 v[176:179], v217 offset:4096
	ds_read_b128 v[180:183], v217 offset:16384
	ds_read_b128 v[184:187], v217 offset:20480
	s_waitcnt lgkmcnt(6)
	v_mfma_f32_32x32x16_bf16 v[4:19], v[140:143], v[132:135], v[4:19]
	v_mfma_f32_32x32x16_bf16 v[68:83], v[140:143], v[136:139], v[68:83]
	v_mfma_f32_32x32x16_bf16 v[20:35], v[144:147], v[132:135], v[20:35]
	v_mfma_f32_32x32x16_bf16 v[84:99], v[144:147], v[136:139], v[84:99]
	v_mfma_f32_32x32x16_bf16 v[36:51], v[148:151], v[132:135], v[36:51]
	v_mfma_f32_32x32x16_bf16 v[100:115], v[148:151], v[136:139], v[100:115]
	v_mfma_f32_32x32x16_bf16 v[52:67], v[158:161], v[132:135], v[52:67]
	v_mfma_f32_32x32x16_bf16 v[116:131], v[158:161], v[136:139], v[116:131]
	s_waitcnt lgkmcnt(0)
	v_mfma_f32_32x32x16_bf16 v[4:19], v[172:175], v[162:165], v[4:19]
	v_mfma_f32_32x32x16_bf16 v[68:83], v[172:175], v[168:171], v[68:83]
	v_mfma_f32_32x32x16_bf16 v[20:35], v[176:179], v[162:165], v[20:35]
	v_mfma_f32_32x32x16_bf16 v[84:99], v[176:179], v[168:171], v[84:99]
	v_mfma_f32_32x32x16_bf16 v[36:51], v[180:183], v[162:165], v[36:51]
	v_mfma_f32_32x32x16_bf16 v[100:115], v[180:183], v[168:171], v[100:115]
	v_mfma_f32_32x32x16_bf16 v[52:67], v[184:187], v[162:165], v[52:67]
	v_mfma_f32_32x32x16_bf16 v[116:131], v[184:187], v[168:171], v[116:131]
	s_waitcnt vmcnt(0) lgkmcnt(0)
	s_barrier
	ds_read_b128 v[132:135], v210 offset:32768
	ds_read_b128 v[136:139], v210 offset:36864
	ds_read_b128 v[140:143], v214 offset:32768
	ds_read_b128 v[144:147], v214 offset:36864
	ds_read_b128 v[148:151], v214 offset:49152
	ds_read_b128 v[158:161], v214 offset:53248
	s_mov_b32 m0, s44
	s_nop 0
	global_load_lds_dwordx4 v208, s[68:69]
	global_load_lds_dwordx4 v209, s[70:71] offset:1024
	global_load_lds_dwordx4 v208, s[72:73] offset:2048
	global_load_lds_dwordx4 v209, s[74:75] offset:3072
	ds_read_b128 v[162:165], v211 offset:32768
	ds_read_b128 v[168:171], v211 offset:36864
	ds_read_b128 v[172:175], v215 offset:32768
	ds_read_b128 v[176:179], v215 offset:36864
	ds_read_b128 v[180:183], v215 offset:49152
	ds_read_b128 v[184:187], v215 offset:53248
	s_waitcnt lgkmcnt(6)
	v_mfma_f32_32x32x16_bf16 v[4:19], v[140:143], v[132:135], v[4:19]
	v_mfma_f32_32x32x16_bf16 v[68:83], v[140:143], v[136:139], v[68:83]
	v_mfma_f32_32x32x16_bf16 v[20:35], v[144:147], v[132:135], v[20:35]
	v_mfma_f32_32x32x16_bf16 v[84:99], v[144:147], v[136:139], v[84:99]
	v_mfma_f32_32x32x16_bf16 v[36:51], v[148:151], v[132:135], v[36:51]
	v_mfma_f32_32x32x16_bf16 v[100:115], v[148:151], v[136:139], v[100:115]
	v_mfma_f32_32x32x16_bf16 v[52:67], v[158:161], v[132:135], v[52:67]
	v_mfma_f32_32x32x16_bf16 v[116:131], v[158:161], v[136:139], v[116:131]
	s_mov_b32 m0, s46
	s_nop 0
	global_load_lds_dwordx4 v208, s[76:77]
	global_load_lds_dwordx4 v209, s[78:79] offset:1024
	global_load_lds_dwordx4 v208, s[80:81] offset:2048
	global_load_lds_dwordx4 v209, s[82:83] offset:3072
	v_add_u32_e32 v208, 0x80, v208
	v_add_u32_e32 v209, 0x80, v209
	ds_read_b128 v[132:135], v212 offset:32768
	ds_read_b128 v[136:139], v212 offset:36864
	ds_read_b128 v[140:143], v216 offset:32768
	ds_read_b128 v[144:147], v216 offset:36864
	ds_read_b128 v[148:151], v216 offset:49152
	ds_read_b128 v[158:161], v216 offset:53248
	s_waitcnt lgkmcnt(6)
; #define MFMA32(a, b, c) __builtin_amdgcn_mfma_f32_32x32x16_bf16((a), (b), (c), 0, 0, 0)
; template <bool SWAP, class Epi>
; DI void gemm_tile(const u16* __restrict__ A, int lda, const u16* __restrict__ Bw, int ldb, int K, char* lds, Epi epi) {
;     ...
;   auto compute = [&](int st) {
;     const char* as = lds + st * GEMM_STAGE;
;     const char* bs = as + 36864;
; #pragma unroll
;     for (int ks = 0; ks < 4; ++ks) {
;       bf16x8 af[2], bfr[2];
; #pragma unroll
;       for (int mi = 0; mi < 2; ++mi) af[mi] = *(const bf16x8*)(as + ((wm * 64 + mi * 32 + r) * 72 + ks * 16 + 8 * h) * 2);
; #pragma unroll
;       for (int ni = 0; ni < 2; ++ni) bfr[ni] = *(const bf16x8*)(bs + ((wn * 64 + ni * 32 + r) * 72 + ks * 16 + 8 * h) * 2);
; #pragma unroll
;       for (int mi = 0; mi < 2; ++mi)
; #pragma unroll
;         for (int ni = 0; ni < 2; ++ni) {
;           if (SWAP) acc[mi][ni] = MFMA32(bfr[ni], af[mi], acc[mi][ni]);
;           else acc[mi][ni] = MFMA32(af[mi], bfr[ni], acc[mi][ni]);
;         }
;     }
;   };
;   gload(0, ra0, rb0);
;   lstore(0, ra0, rb0);
;   gload(1, ra1, rb1);
;   __syncthreads();
;   for (int kt = 0; kt < nk; kt += 2) {
;     if (kt + 2 < nk) gload(kt + 2, ra0, rb0);
;     compute(0);
;     lstore(1, ra1, rb1);
;     __syncthreads();
;     if (kt + 3 < nk) gload(kt + 3, ra1, rb1);
;     compute(1);
;     if (kt + 2 < nk) lstore(0, ra0, rb0);
;     __syncthreads();
	v_mfma_f32_32x32x16_bf16 v[4:19], v[172:175], v[162:165], v[4:19]
	v_mfma_f32_32x32x16_bf16 v[68:83], v[172:175], v[168:171], v[68:83]
	v_mfma_f32_32x32x16_bf16 v[20:35], v[176:179], v[162:165], v[20:35]
	v_mfma_f32_32x32x16_bf16 v[84:99], v[176:179], v[168:171], v[84:99]
	v_mfma_f32_32x32x16_bf16 v[36:51], v[180:183], v[162:165], v[36:51]
	v_mfma_f32_32x32x16_bf16 v[100:115], v[180:183], v[168:171], v[100:115]
	v_mfma_f32_32x32x16_bf16 v[52:67], v[184:187], v[162:165], v[52:67]
	v_mfma_f32_32x32x16_bf16 v[116:131], v[184:187], v[168:171], v[116:131]
	ds_read_b128 v[162:165], v213 offset:32768
	ds_read_b128 v[168:171], v213 offset:36864
	ds_read_b128 v[172:175], v217 offset:32768
	ds_read_b128 v[176:179], v217 offset:36864
	ds_read_b128 v[180:183], v217 offset:49152
	ds_read_b128 v[184:187], v217 offset:53248
	s_waitcnt lgkmcnt(6)
	v_mfma_f32_32x32x16_bf16 v[4:19], v[140:143], v[132:135], v[4:19]
	v_mfma_f32_32x32x16_bf16 v[68:83], v[140:143], v[136:139], v[68:83]
	v_mfma_f32_32x32x16_bf16 v[20:35], v[144:147], v[132:135], v[20:35]
	v_mfma_f32_32x32x16_bf16 v[84:99], v[144:147], v[136:139], v[84:99]
	v_mfma_f32_32x32x16_bf16 v[36:51], v[148:151], v[132:135], v[36:51]
	v_mfma_f32_32x32x16_bf16 v[100:115], v[148:151], v[136:139], v[100:115]
	v_mfma_f32_32x32x16_bf16 v[52:67], v[158:161], v[132:135], v[52:67]
	v_mfma_f32_32x32x16_bf16 v[116:131], v[158:161], v[136:139], v[116:131]
	s_waitcnt lgkmcnt(0)
	v_mfma_f32_32x32x16_bf16 v[4:19], v[172:175], v[162:165], v[4:19]
	v_mfma_f32_32x32x16_bf16 v[68:83], v[172:175], v[168:171], v[68:83]
	v_mfma_f32_32x32x16_bf16 v[20:35], v[176:179], v[162:165], v[20:35]
	v_mfma_f32_32x32x16_bf16 v[84:99], v[176:179], v[168:171], v[84:99]
	v_mfma_f32_32x32x16_bf16 v[36:51], v[180:183], v[162:165], v[36:51]
	v_mfma_f32_32x32x16_bf16 v[100:115], v[180:183], v[168:171], v[100:115]
	v_mfma_f32_32x32x16_bf16 v[52:67], v[184:187], v[162:165], v[52:67]
	v_mfma_f32_32x32x16_bf16 v[116:131], v[184:187], v[168:171], v[116:131]
	s_waitcnt vmcnt(0) lgkmcnt(0)
	s_barrier
	ds_read_b128 v[132:135], v210 offset:0
	ds_read_b128 v[136:139], v210 offset:4096
	ds_read_b128 v[140:143], v214 offset:0
	ds_read_b128 v[144:147], v214 offset:4096
	ds_read_b128 v[148:151], v214 offset:16384
	ds_read_b128 v[158:161], v214 offset:20480
	s_mov_b32 m0, s45
	s_nop 0
	global_load_lds_dwordx4 v208, s[68:69]
	global_load_lds_dwordx4 v209, s[70:71] offset:1024
	global_load_lds_dwordx4 v208, s[72:73] offset:2048
	global_load_lds_dwordx4 v209, s[74:75] offset:3072
	ds_read_b128 v[162:165], v211 offset:0
	ds_read_b128 v[168:171], v211 offset:4096
	ds_read_b128 v[172:175], v215 offset:0
	ds_read_b128 v[176:179], v215 offset:4096
	ds_read_b128 v[180:183], v215 offset:16384
	ds_read_b128 v[184:187], v215 offset:20480
	s_waitcnt lgkmcnt(6)
	v_mfma_f32_32x32x16_bf16 v[4:19], v[140:143], v[132:135], v[4:19]
	v_mfma_f32_32x32x16_bf16 v[68:83], v[140:143], v[136:139], v[68:83]
	v_mfma_f32_32x32x16_bf16 v[20:35], v[144:147], v[132:135], v[20:35]
	v_mfma_f32_32x32x16_bf16 v[84:99], v[144:147], v[136:139], v[84:99]
	v_mfma_f32_32x32x16_bf16 v[36:51], v[148:151], v[132:135], v[36:51]
	v_mfma_f32_32x32x16_bf16 v[100:115], v[148:151], v[136:139], v[100:115]
	v_mfma_f32_32x32x16_bf16 v[52:67], v[158:161], v[132:135], v[52:67]
	v_mfma_f32_32x32x16_bf16 v[116:131], v[158:161], v[136:139], v[116:131]
	s_mov_b32 m0, s47
	s_nop 0
	global_load_lds_dwordx4 v208, s[76:77]
	global_load_lds_dwordx4 v209, s[78:79] offset:1024
	global_load_lds_dwordx4 v208, s[80:81] offset:2048
	global_load_lds_dwordx4 v209, s[82:83] offset:3072
	v_add_u32_e32 v208, 0x80, v208
	v_add_u32_e32 v209, 0x80, v209
	ds_read_b128 v[132:135], v212 offset:0
	ds_read_b128 v[136:139], v212 offset:4096
	ds_read_b128 v[140:143], v216 offset:0
	ds_read_b128 v[144:147], v216 offset:4096
	ds_read_b128 v[148:151], v216 offset:16384
	ds_read_b128 v[158:161], v216 offset:20480
	s_waitcnt lgkmcnt(6)
	v_mfma_f32_32x32x16_bf16 v[4:19], v[172:175], v[162:165], v[4:19]
	v_mfma_f32_32x32x16_bf16 v[68:83], v[172:175], v[168:171], v[68:83]
	v_mfma_f32_32x32x16_bf16 v[20:35], v[176:179], v[162:165], v[20:35]
	v_mfma_f32_32x32x16_bf16 v[84:99], v[176:179], v[168:171], v[84:99]
	v_mfma_f32_32x32x16_bf16 v[36:51], v[180:183], v[162:165], v[36:51]
	v_mfma_f32_32x32x16_bf16 v[100:115], v[180:183], v[168:171], v[100:115]
	v_mfma_f32_32x32x16_bf16 v[52:67], v[184:187], v[162:165], v[52:67]
	v_mfma_f32_32x32x16_bf16 v[116:131], v[184:187], v[168:171], v[116:131]
	ds_read_b128 v[162:165], v213 offset:0
	ds_read_b128 v[168:171], v213 offset:4096
	ds_read_b128 v[172:175], v217 offset:0
	ds_read_b128 v[176:179], v217 offset:4096
	ds_read_b128 v[180:183], v217 offset:16384
	ds_read_b128 v[184:187], v217 offset:20480
	s_waitcnt lgkmcnt(6)
	v_mfma_f32_32x32x16_bf16 v[4:19], v[140:143], v[132:135], v[4:19]
	v_mfma_f32_32x32x16_bf16 v[68:83], v[140:143], v[136:139], v[68:83]
	v_mfma_f32_32x32x16_bf16 v[20:35], v[144:147], v[132:135], v[20:35]
	v_mfma_f32_32x32x16_bf16 v[84:99], v[144:147], v[136:139], v[84:99]
	v_mfma_f32_32x32x16_bf16 v[36:51], v[148:151], v[132:135], v[36:51]
	v_mfma_f32_32x32x16_bf16 v[100:115], v[148:151], v[136:139], v[100:115]
	v_mfma_f32_32x32x16_bf16 v[52:67], v[158:161], v[132:135], v[52:67]
	v_mfma_f32_32x32x16_bf16 v[116:131], v[158:161], v[136:139], v[116:131]
	s_waitcnt lgkmcnt(0)
	v_mfma_f32_32x32x16_bf16 v[4:19], v[172:175], v[162:165], v[4:19]
	v_mfma_f32_32x32x16_bf16 v[68:83], v[172:175], v[168:171], v[68:83]
	v_mfma_f32_32x32x16_bf16 v[20:35], v[176:179], v[162:165], v[20:35]
	v_mfma_f32_32x32x16_bf16 v[84:99], v[176:179], v[168:171], v[84:99]
	v_mfma_f32_32x32x16_bf16 v[36:51], v[180:183], v[162:165], v[36:51]
	v_mfma_f32_32x32x16_bf16 v[100:115], v[180:183], v[168:171], v[100:115]
	v_mfma_f32_32x32x16_bf16 v[52:67], v[184:187], v[162:165], v[52:67]
	v_mfma_f32_32x32x16_bf16 v[116:131], v[184:187], v[168:171], v[116:131]
	s_waitcnt vmcnt(0) lgkmcnt(0)
	s_barrier
; #define MFMA32(a, b, c) __builtin_amdgcn_mfma_f32_32x32x16_bf16((a), (b), (c), 0, 0, 0)
; template <bool SWAP, class Epi>
; DI void gemm_tile(const u16* __restrict__ A, int lda, const u16* __restrict__ Bw, int ldb, int K, char* lds, Epi epi) {
;     ...
;   auto compute = [&](int st) {
;     const char* as = lds + st * GEMM_STAGE;
;     const char* bs = as + 36864;
; #pragma unroll
;     for (int ks = 0; ks < 4; ++ks) {
;       bf16x8 af[2], bfr[2];
; #pragma unroll
;       for (int mi = 0; mi < 2; ++mi) af[mi] = *(const bf16x8*)(as + ((wm * 64 + mi * 32 + r) * 72 + ks * 16 + 8 * h) * 2);
; #pragma unroll
;       for (int ni = 0; ni < 2; ++ni) bfr[ni] = *(const bf16x8*)(bs + ((wn * 64 + ni * 32 + r) * 72 + ks * 16 + 8 * h) * 2);
; #pragma unroll
;       for (int mi = 0; mi < 2; ++mi)
; #pragma unroll
;         for (int ni = 0; ni < 2; ++ni) {
;           if (SWAP) acc[mi][ni] = MFMA32(bfr[ni], af[mi], acc[mi][ni]);
;           else acc[mi][ni] = MFMA32(af[mi], bfr[ni], acc[mi][ni]);
;         }
;     }
;   };
;   gload(0, ra0, rb0);
;   lstore(0, ra0, rb0);
;   gload(1, ra1, rb1);
;   __syncthreads();
;   for (int kt = 0; kt < nk; kt += 2) {
;     if (kt + 2 < nk) gload(kt + 2, ra0, rb0);
;     compute(0);
;     lstore(1, ra1, rb1);
;     __syncthreads();
;     if (kt + 3 < nk) gload(kt + 3, ra1, rb1);
;     compute(1);
;     if (kt + 2 < nk) lstore(0, ra0, rb0);
;     __syncthreads();
	ds_read_b128 v[132:135], v210 offset:32768
	ds_read_b128 v[136:139], v210 offset:36864
	ds_read_b128 v[140:143], v214 offset:32768
	ds_read_b128 v[144:147], v214 offset:36864
	ds_read_b128 v[148:151], v214 offset:49152
	ds_read_b128 v[158:161], v214 offset:53248
	s_mov_b32 m0, s44
	s_nop 0
	global_load_lds_dwordx4 v208, s[68:69]
	global_load_lds_dwordx4 v209, s[70:71] offset:1024
	global_load_lds_dwordx4 v208, s[72:73] offset:2048
	global_load_lds_dwordx4 v209, s[74:75] offset:3072
	ds_read_b128 v[162:165], v211 offset:32768
	ds_read_b128 v[168:171], v211 offset:36864
	ds_read_b128 v[172:175], v215 offset:32768
	ds_read_b128 v[176:179], v215 offset:36864
	ds_read_b128 v[180:183], v215 offset:49152
	ds_read_b128 v[184:187], v215 offset:53248
	s_waitcnt lgkmcnt(6)
	v_mfma_f32_32x32x16_bf16 v[4:19], v[140:143], v[132:135], v[4:19]
	v_mfma_f32_32x32x16_bf16 v[68:83], v[140:143], v[136:139], v[68:83]
	v_mfma_f32_32x32x16_bf16 v[20:35], v[144:147], v[132:135], v[20:35]
	v_mfma_f32_32x32x16_bf16 v[84:99], v[144:147], v[136:139], v[84:99]
	v_mfma_f32_32x32x16_bf16 v[36:51], v[148:151], v[132:135], v[36:51]
	v_mfma_f32_32x32x16_bf16 v[100:115], v[148:151], v[136:139], v[100:115]
	v_mfma_f32_32x32x16_bf16 v[52:67], v[158:161], v[132:135], v[52:67]
	v_mfma_f32_32x32x16_bf16 v[116:131], v[158:161], v[136:139], v[116:131]
	s_mov_b32 m0, s46
	s_nop 0
	global_load_lds_dwordx4 v208, s[76:77]
	global_load_lds_dwordx4 v209, s[78:79] offset:1024
	global_load_lds_dwordx4 v208, s[80:81] offset:2048
	global_load_lds_dwordx4 v209, s[82:83] offset:3072
	v_add_u32_e32 v208, 0x80, v208
	v_add_u32_e32 v209, 0x80, v209
	ds_read_b128 v[132:135], v212 offset:32768
	ds_read_b128 v[136:139], v212 offset:36864
	ds_read_b128 v[140:143], v216 offset:32768
	ds_read_b128 v[144:147], v216 offset:36864
	ds_read_b128 v[148:151], v216 offset:49152
	ds_read_b128 v[158:161], v216 offset:53248
	s_waitcnt lgkmcnt(6)
	v_mfma_f32_32x32x16_bf16 v[4:19], v[172:175], v[162:165], v[4:19]
	v_mfma_f32_32x32x16_bf16 v[68:83], v[172:175], v[168:171], v[68:83]
	v_mfma_f32_32x32x16_bf16 v[20:35], v[176:179], v[162:165], v[20:35]
	v_mfma_f32_32x32x16_bf16 v[84:99], v[176:179], v[168:171], v[84:99]
	v_mfma_f32_32x32x16_bf16 v[36:51], v[180:183], v[162:165], v[36:51]
	v_mfma_f32_32x32x16_bf16 v[100:115], v[180:183], v[168:171], v[100:115]
	v_mfma_f32_32x32x16_bf16 v[52:67], v[184:187], v[162:165], v[52:67]
	v_mfma_f32_32x32x16_bf16 v[116:131], v[184:187], v[168:171], v[116:131]
	ds_read_b128 v[162:165], v213 offset:32768
	ds_read_b128 v[168:171], v213 offset:36864
	ds_read_b128 v[172:175], v217 offset:32768
	ds_read_b128 v[176:179], v217 offset:36864
	ds_read_b128 v[180:183], v217 offset:49152
	ds_read_b128 v[184:187], v217 offset:53248
	s_waitcnt lgkmcnt(6)
	v_mfma_f32_32x32x16_bf16 v[4:19], v[140:143], v[132:135], v[4:19]
	v_mfma_f32_32x32x16_bf16 v[68:83], v[140:143], v[136:139], v[68:83]
	v_mfma_f32_32x32x16_bf16 v[20:35], v[144:147], v[132:135], v[20:35]
	v_mfma_f32_32x32x16_bf16 v[84:99], v[144:147], v[136:139], v[84:99]
	v_mfma_f32_32x32x16_bf16 v[36:51], v[148:151], v[132:135], v[36:51]
	v_mfma_f32_32x32x16_bf16 v[100:115], v[148:151], v[136:139], v[100:115]
	v_mfma_f32_32x32x16_bf16 v[52:67], v[158:161], v[132:135], v[52:67]
	v_mfma_f32_32x32x16_bf16 v[116:131], v[158:161], v[136:139], v[116:131]
	s_waitcnt lgkmcnt(0)
	v_mfma_f32_32x32x16_bf16 v[4:19], v[172:175], v[162:165], v[4:19]
	v_mfma_f32_32x32x16_bf16 v[68:83], v[172:175], v[168:171], v[68:83]
	v_mfma_f32_32x32x16_bf16 v[20:35], v[176:179], v[162:165], v[20:35]
	v_mfma_f32_32x32x16_bf16 v[84:99], v[176:179], v[168:171], v[84:99]
	v_mfma_f32_32x32x16_bf16 v[36:51], v[180:183], v[162:165], v[36:51]
	v_mfma_f32_32x32x16_bf16 v[100:115], v[180:183], v[168:171], v[100:115]
	v_mfma_f32_32x32x16_bf16 v[52:67], v[184:187], v[162:165], v[52:67]
	v_mfma_f32_32x32x16_bf16 v[116:131], v[184:187], v[168:171], v[116:131]
	s_waitcnt vmcnt(0) lgkmcnt(0)
	s_barrier
	ds_read_b128 v[132:135], v210 offset:0
	ds_read_b128 v[136:139], v210 offset:4096
	ds_read_b128 v[140:143], v214 offset:0
	ds_read_b128 v[144:147], v214 offset:4096
	ds_read_b128 v[148:151], v214 offset:16384
	ds_read_b128 v[158:161], v214 offset:20480
	s_mov_b32 m0, s45
	s_nop 0
	global_load_lds_dwordx4 v208, s[68:69]
	global_load_lds_dwordx4 v209, s[70:71] offset:1024
	global_load_lds_dwordx4 v208, s[72:73] offset:2048
	global_load_lds_dwordx4 v209, s[74:75] offset:3072
	ds_read_b128 v[162:165], v211 offset:0
	ds_read_b128 v[168:171], v211 offset:4096
	ds_read_b128 v[172:175], v215 offset:0
	ds_read_b128 v[176:179], v215 offset:4096
	ds_read_b128 v[180:183], v215 offset:16384
	ds_read_b128 v[184:187], v215 offset:20480
	s_waitcnt lgkmcnt(6)
	v_mfma_f32_32x32x16_bf16 v[4:19], v[140:143], v[132:135], v[4:19]
	v_mfma_f32_32x32x16_bf16 v[68:83], v[140:143], v[136:139], v[68:83]
	v_mfma_f32_32x32x16_bf16 v[20:35], v[144:147], v[132:135], v[20:35]
	v_mfma_f32_32x32x16_bf16 v[84:99], v[144:147], v[136:139], v[84:99]
	v_mfma_f32_32x32x16_bf16 v[36:51], v[148:151], v[132:135], v[36:51]
	v_mfma_f32_32x32x16_bf16 v[100:115], v[148:151], v[136:139], v[100:115]
	v_mfma_f32_32x32x16_bf16 v[52:67], v[158:161], v[132:135], v[52:67]
	v_mfma_f32_32x32x16_bf16 v[116:131], v[158:161], v[136:139], v[116:131]
	s_mov_b32 m0, s47
	s_nop 0
	global_load_lds_dwordx4 v208, s[76:77]
	global_load_lds_dwordx4 v209, s[78:79] offset:1024
	global_load_lds_dwordx4 v208, s[80:81] offset:2048
	global_load_lds_dwordx4 v209, s[82:83] offset:3072
	v_add_u32_e32 v208, 0x80, v208
	v_add_u32_e32 v209, 0x80, v209
	ds_read_b128 v[132:135], v212 offset:0
	ds_read_b128 v[136:139], v212 offset:4096
	ds_read_b128 v[140:143], v216 offset:0
	ds_read_b128 v[144:147], v216 offset:4096
	ds_read_b128 v[148:151], v216 offset:16384
	ds_read_b128 v[158:161], v216 offset:20480
	s_waitcnt lgkmcnt(6)
; template <bool SWAP, class Epi>
; DI void gemm_tile(const u16* __restrict__ A, int lda, const u16* __restrict__ Bw, int ldb, int K, char* lds, Epi epi) {
;     ...
;   const u16* ap = A + (size_t)lrow * lda + lkc * 8;
;   const u16* bp = Bw + (size_t)lrow * ldb + lkc * 8;
;   const int nk = K >> 6;
;   auto gload = [&](int kt, u32x4* ra, u32x4* rb) {
; #pragma unroll
;     for (int j = 0; j < 4; ++j) ra[j] = *(const u32x4*)(ap + (size_t)(64 * j) * lda + kt * 64);
; #pragma unroll
;     for (int j = 0; j < 2; ++j) rb[j] = *(const u32x4*)(bp + (size_t)(64 * j) * ldb + kt * 64);
;   };
;     ...
;   for (int kt = 0; kt < nk; kt += 2) {
;     if (kt + 2 < nk) gload(kt + 2, ra0, rb0);
;     compute(0);
;     lstore(1, ra1, rb1);
;     __syncthreads();
;     if (kt + 3 < nk) gload(kt + 3, ra1, rb1);
;     compute(1);
;     if (kt + 2 < nk) lstore(0, ra0, rb0);
;     __syncthreads();
	v_mfma_f32_32x32x16_bf16 v[4:19], v[172:175], v[162:165], v[4:19]
	v_mfma_f32_32x32x16_bf16 v[68:83], v[172:175], v[168:171], v[68:83]
	v_mfma_f32_32x32x16_bf16 v[20:35], v[176:179], v[162:165], v[20:35]
	v_mfma_f32_32x32x16_bf16 v[84:99], v[176:179], v[168:171], v[84:99]
	v_mfma_f32_32x32x16_bf16 v[36:51], v[180:183], v[162:165], v[36:51]
	v_mfma_f32_32x32x16_bf16 v[100:115], v[180:183], v[168:171], v[100:115]
	v_mfma_f32_32x32x16_bf16 v[52:67], v[184:187], v[162:165], v[52:67]
	v_mfma_f32_32x32x16_bf16 v[116:131], v[184:187], v[168:171], v[116:131]
	ds_read_b128 v[162:165], v213 offset:0
	ds_read_b128 v[168:171], v213 offset:4096
	ds_read_b128 v[172:175], v217 offset:0
	ds_read_b128 v[176:179], v217 offset:4096
	ds_read_b128 v[180:183], v217 offset:16384
	ds_read_b128 v[184:187], v217 offset:20480
	s_waitcnt lgkmcnt(6)
	v_mfma_f32_32x32x16_bf16 v[4:19], v[140:143], v[132:135], v[4:19]
	v_mfma_f32_32x32x16_bf16 v[68:83], v[140:143], v[136:139], v[68:83]
	v_mfma_f32_32x32x16_bf16 v[20:35], v[144:147], v[132:135], v[20:35]
	v_mfma_f32_32x32x16_bf16 v[84:99], v[144:147], v[136:139], v[84:99]
	v_mfma_f32_32x32x16_bf16 v[36:51], v[148:151], v[132:135], v[36:51]
	v_mfma_f32_32x32x16_bf16 v[100:115], v[148:151], v[136:139], v[100:115]
	v_mfma_f32_32x32x16_bf16 v[52:67], v[158:161], v[132:135], v[52:67]
	v_mfma_f32_32x32x16_bf16 v[116:131], v[158:161], v[136:139], v[116:131]
	s_waitcnt lgkmcnt(0)
	v_mfma_f32_32x32x16_bf16 v[4:19], v[172:175], v[162:165], v[4:19]
	v_mfma_f32_32x32x16_bf16 v[68:83], v[172:175], v[168:171], v[68:83]
	v_mfma_f32_32x32x16_bf16 v[20:35], v[176:179], v[162:165], v[20:35]
	v_mfma_f32_32x32x16_bf16 v[84:99], v[176:179], v[168:171], v[84:99]
	v_mfma_f32_32x32x16_bf16 v[36:51], v[180:183], v[162:165], v[36:51]
	v_mfma_f32_32x32x16_bf16 v[100:115], v[180:183], v[168:171], v[100:115]
	v_mfma_f32_32x32x16_bf16 v[52:67], v[184:187], v[162:165], v[52:67]
	v_mfma_f32_32x32x16_bf16 v[116:131], v[184:187], v[168:171], v[116:131]
	s_waitcnt vmcnt(0) lgkmcnt(0)
	s_barrier
	ds_read_b128 v[132:135], v210 offset:32768
	ds_read_b128 v[136:139], v210 offset:36864
	ds_read_b128 v[140:143], v214 offset:32768
	ds_read_b128 v[144:147], v214 offset:36864
	ds_read_b128 v[148:151], v214 offset:49152
	ds_read_b128 v[158:161], v214 offset:53248
	ds_read_b128 v[162:165], v211 offset:32768
	ds_read_b128 v[168:171], v211 offset:36864
	ds_read_b128 v[172:175], v215 offset:32768
	ds_read_b128 v[176:179], v215 offset:36864
	ds_read_b128 v[180:183], v215 offset:49152
	ds_read_b128 v[184:187], v215 offset:53248
	s_waitcnt lgkmcnt(6)
	v_mfma_f32_32x32x16_bf16 v[4:19], v[140:143], v[132:135], v[4:19]
	v_mfma_f32_32x32x16_bf16 v[68:83], v[140:143], v[136:139], v[68:83]
	v_mfma_f32_32x32x16_bf16 v[20:35], v[144:147], v[132:135], v[20:35]
	v_mfma_f32_32x32x16_bf16 v[84:99], v[144:147], v[136:139], v[84:99]
	v_mfma_f32_32x32x16_bf16 v[36:51], v[148:151], v[132:135], v[36:51]
	v_mfma_f32_32x32x16_bf16 v[100:115], v[148:151], v[136:139], v[100:115]
	v_mfma_f32_32x32x16_bf16 v[52:67], v[158:161], v[132:135], v[52:67]
	v_mfma_f32_32x32x16_bf16 v[116:131], v[158:161], v[136:139], v[116:131]
	ds_read_b128 v[132:135], v212 offset:32768
	ds_read_b128 v[136:139], v212 offset:36864
	ds_read_b128 v[140:143], v216 offset:32768
	ds_read_b128 v[144:147], v216 offset:36864
	ds_read_b128 v[148:151], v216 offset:49152
	ds_read_b128 v[158:161], v216 offset:53248
	s_waitcnt lgkmcnt(6)
	v_mfma_f32_32x32x16_bf16 v[4:19], v[172:175], v[162:165], v[4:19]
	v_mfma_f32_32x32x16_bf16 v[68:83], v[172:175], v[168:171], v[68:83]
	v_mfma_f32_32x32x16_bf16 v[20:35], v[176:179], v[162:165], v[20:35]
	v_mfma_f32_32x32x16_bf16 v[84:99], v[176:179], v[168:171], v[84:99]
	v_mfma_f32_32x32x16_bf16 v[36:51], v[180:183], v[162:165], v[36:51]
	v_mfma_f32_32x32x16_bf16 v[100:115], v[180:183], v[168:171], v[100:115]
	v_mfma_f32_32x32x16_bf16 v[52:67], v[184:187], v[162:165], v[52:67]
	v_mfma_f32_32x32x16_bf16 v[116:131], v[184:187], v[168:171], v[116:131]
	ds_read_b128 v[162:165], v213 offset:32768
	ds_read_b128 v[168:171], v213 offset:36864
	ds_read_b128 v[172:175], v217 offset:32768
	ds_read_b128 v[176:179], v217 offset:36864
	ds_read_b128 v[180:183], v217 offset:49152
	ds_read_b128 v[184:187], v217 offset:53248
	s_waitcnt lgkmcnt(6)
	v_mfma_f32_32x32x16_bf16 v[4:19], v[140:143], v[132:135], v[4:19]
	v_mfma_f32_32x32x16_bf16 v[68:83], v[140:143], v[136:139], v[68:83]
	v_mfma_f32_32x32x16_bf16 v[20:35], v[144:147], v[132:135], v[20:35]
	v_mfma_f32_32x32x16_bf16 v[84:99], v[144:147], v[136:139], v[84:99]
	v_mfma_f32_32x32x16_bf16 v[36:51], v[148:151], v[132:135], v[36:51]
	v_mfma_f32_32x32x16_bf16 v[100:115], v[148:151], v[136:139], v[100:115]
	v_mfma_f32_32x32x16_bf16 v[52:67], v[158:161], v[132:135], v[52:67]
	v_mfma_f32_32x32x16_bf16 v[116:131], v[158:161], v[136:139], v[116:131]
	s_waitcnt lgkmcnt(0)
	v_mfma_f32_32x32x16_bf16 v[4:19], v[172:175], v[162:165], v[4:19]
	v_mfma_f32_32x32x16_bf16 v[68:83], v[172:175], v[168:171], v[68:83]
	v_mfma_f32_32x32x16_bf16 v[20:35], v[176:179], v[162:165], v[20:35]
	v_mfma_f32_32x32x16_bf16 v[84:99], v[176:179], v[168:171], v[84:99]
	v_mfma_f32_32x32x16_bf16 v[36:51], v[180:183], v[162:165], v[36:51]
	v_mfma_f32_32x32x16_bf16 v[100:115], v[180:183], v[168:171], v[100:115]
	v_mfma_f32_32x32x16_bf16 v[52:67], v[184:187], v[162:165], v[52:67]
	v_mfma_f32_32x32x16_bf16 v[116:131], v[184:187], v[168:171], v[116:131]
	s_waitcnt lgkmcnt(0)
	s_barrier
	s_cmp_gt_u32 s41, 5
	s_cbranch_scc1 .Lpp_nopf
	s_add_i32 s0, s101, 32
	s_cmpk_ge_u32 s0, 0xc6
	s_cbranch_scc1 .Lpp_nopf
	s_mul_i32 s1, s0, 0x5556
	s_lshr_b32 s1, s1, 16
	s_mul_i32 s4, s1, 3
	s_sub_i32 s0, s0, s4
	s_mul_i32 s0, s0, 6
	s_add_i32 s0, s0, s41
	s_lshl_b32 s4, s0, 1
	s_cmp_gt_u32 s0, 1
	s_cselect_b32 s5, 4, 0
	s_add_i32 s0, s4, s5
	v_readlane_b32 s4, v241, 26
	v_readlane_b32 s5, v241, 27
	s_lshl_b32 s1, s1, 19
	s_add_u32 s4, s4, s1
	s_addc_u32 s5, s5, 0
	s_lshl_b32 s0, s0, 18
	s_add_u32 s6, s18, s0
	s_addc_u32 s7, s19, 0
	s_lshl_b32 s0, s3, 16
	s_add_u32 s68, s4, s0
	s_addc_u32 s69, s5, 0
	s_add_u32 s70, s68, 0x3c00
	s_addc_u32 s71, s69, 0
	s_add_u32 s72, s70, 0x3c00
	s_addc_u32 s73, s71, 0
	s_add_u32 s74, s72, 0x3c00
	s_addc_u32 s75, s73, 0
	s_add_u32 s76, s6, s0
	s_addc_u32 s77, s7, 0
	s_add_u32 s78, s76, 0x3c00
	s_addc_u32 s79, s77, 0
	s_add_u32 s80, s78, 0x3c00
	s_addc_u32 s81, s79, 0
	s_add_u32 s82, s80, 0x3c00
	s_addc_u32 s83, s81, 0
	v_mov_b32_e32 v208, v220
	v_xor_b32_e32 v209, 64, v220
	s_mov_b32 m0, s44
	s_nop 0
	global_load_lds_dwordx4 v208, s[68:69]
	global_load_lds_dwordx4 v209, s[70:71] offset:1024
	global_load_lds_dwordx4 v208, s[72:73] offset:2048
	global_load_lds_dwordx4 v209, s[74:75] offset:3072
	s_mov_b32 m0, s46
	s_nop 0
	global_load_lds_dwordx4 v208, s[76:77]
	global_load_lds_dwordx4 v209, s[78:79] offset:1024
	global_load_lds_dwordx4 v208, s[80:81] offset:2048
	global_load_lds_dwordx4 v209, s[82:83] offset:3072
	s_mov_b32 s100, 1
